# GEMM K-loops: first 4 MFMAs of each compute segment issue before the segment barrier (matrix pipe busy across the hand-off)
# speedup vs baseline: 1.0079x; 1.0060x over previous
; #define PG8_STAGE(bufoff, gbase, voff) do { _Pragma("unroll") for (int _i = 0; _i < 2; ++_i) \
;         __builtin_amdgcn_global_load_lds((const unsigned*)((const char*)(gbase) + (voff)[_i]), (PG8_LAS unsigned*)(lds + (bufoff) + ldsw + _i * 8192), 16, 0, 0); } while (0)
; #define PG8_LDA(dst, b, h) do { _Pragma("unroll") for (int m = 0; m < 4; ++m) _Pragma("unroll") for (int k = 0; k < 2; ++k) dst[m][k] = *(const PG8_LAS bf16x8*)(lds + PG8_SA(b, h) + aoff + m * 2048 + k * 1024); } while (0)
; #define PG8_LDB(dst, b, h) do { _Pragma("unroll") for (int n = 0; n < 2; ++n) _Pragma("unroll") for (int k = 0; k < 2; ++k) dst[n][k] = *(const PG8_LAS bf16x8*)(lds + PG8_SB(b, h) + boff + n * 2048 + k * 1024); } while (0)
; #define PG8_MMA(ai, bj, At, Bt) do { __builtin_amdgcn_s_setprio(1); _Pragma("unroll") for (int m = 0; m < 4; ++m) _Pragma("unroll") for (int n = 0; n < 2; ++n) _Pragma("unroll") for (int k = 0; k < 2; ++k) \
;         acc[ai][bj][m][n] = __builtin_amdgcn_mfma_f32_16x16x32_bf16(Bt[n][k], At[m][k], acc[ai][bj][m][n], 0, 0, 0); __builtin_amdgcn_s_setprio(0); } while (0)
; #define PG8_WAIT_V(n) asm volatile("s_waitcnt vmcnt(" #n ")" ::: "memory")
; #define PG8_WAIT_L(n) asm volatile("s_waitcnt lgkmcnt(" #n ")" ::: "memory")
; #define PG8_BAR __builtin_amdgcn_s_barrier()
; #define PG8_SCHED __builtin_amdgcn_sched_barrier(0)
; template <class Epi, class Sched, bool ALIGN_EPI = false, bool SP2 = false, bool ABLK = false, bool BBLK = false>
; __device__ __forceinline__ void gemm_phase(PG8_LAS unsigned char* lds, const Gemm g, const Sched& S, const Epi& E) {
;     ...
;             PG8_LDB(B0, 0, 0); PG8_LDB(B1, 0, 1); PG8_SCHED; PG8_LDA(At, 0, 0); PG8_STAGE(PG8_SA(1, 1), a1 + hstepA, voffA);
;             PG8_WAIT_V(8); PG8_WAIT_L(0); PG8_BAR; PG8_MMA(0, 0, At, B0); PG8_MMA(0, 1, At, B1); PG8_BAR; PG8_SCHED;
;             PG8_LDA(At, 0, 1); PG8_STAGE(PG8_SB(0, 0), b2, voffB); PG8_STAGE(PG8_SB(0, 1), b2 + hstepB, voffB); PG8_STAGE(PG8_SA(0, 0), a2, voffA);
;             PG8_WAIT_V(8); PG8_WAIT_L(0); PG8_BAR; PG8_MMA(1, 0, At, B0); PG8_MMA(1, 1, At, B1); PG8_BAR; PG8_SCHED;
.LBB0_185:
	s_add_u32 s13, s20, 0x4000
	s_addc_u32 s22, s21, 0
	s_cmp_eq_u32 vcc_hi, 28
	s_cselect_b32 s26, s70, s13
	s_cselect_b32 s27, s9, s22
	s_cselect_b32 s24, s71, s77
	s_cselect_b32 s25, s7, vcc_lo
	s_add_u32 s22, s26, 0x8000
	s_addc_u32 s23, s27, 0
	s_add_i32 s13, 0, 0x10000
	v_add_u32_e32 v36, s13, v160
	s_add_i32 s88, 0, 0x14000
	ds_read_b128 v[152:155], v36
	ds_read_b128 v[156:159], v36 offset:1024
	ds_read_b128 v[162:165], v36 offset:2048
	ds_read_b128 v[166:169], v36 offset:3072
	v_add_u32_e32 v36, s88, v160
	ds_read_b128 v[170:173], v36
	ds_read_b128 v[174:177], v36 offset:1024
	ds_read_b128 v[178:181], v36 offset:2048
	ds_read_b128 v[182:185], v36 offset:3072
	s_add_i32 m0, s19, 0xc000
	ds_read_b128 v[186:189], v161
	ds_read_b128 v[190:193], v161 offset:1024
	ds_read_b128 v[194:197], v161 offset:2048
	ds_read_b128 v[198:201], v161 offset:3072
	ds_read_b128 v[202:205], v161 offset:4096
	ds_read_b128 v[206:209], v161 offset:5120
	ds_read_b128 v[210:213], v161 offset:6144
	ds_read_b128 v[214:217], v161 offset:7168
	global_load_lds_dwordx4 v148, s[20:21]
	s_add_i32 m0, s19, 0xe000
	s_nop 0
	global_load_lds_dwordx4 v150, s[20:21]
	s_waitcnt vmcnt(8)
	s_waitcnt lgkmcnt(0)
	v_mfma_f32_16x16x32_bf16 v[132:135], v[152:155], v[186:189], v[132:135]
	v_mfma_f32_16x16x32_bf16 v[128:131], v[162:165], v[186:189], v[128:131]
	v_mfma_f32_16x16x32_bf16 v[116:119], v[152:155], v[194:197], v[116:119]
	v_mfma_f32_16x16x32_bf16 v[112:115], v[162:165], v[194:197], v[112:115]
	s_barrier
	s_setprio 1
	v_mfma_f32_16x16x32_bf16 v[100:103], v[152:155], v[202:205], v[100:103]
	v_mfma_f32_16x16x32_bf16 v[96:99], v[162:165], v[202:205], v[96:99]
	v_mfma_f32_16x16x32_bf16 v[84:87], v[152:155], v[210:213], v[84:87]
	v_mfma_f32_16x16x32_bf16 v[80:83], v[162:165], v[210:213], v[80:83]
	v_mfma_f32_16x16x32_bf16 v[132:135], v[156:159], v[190:193], v[132:135]
	v_mfma_f32_16x16x32_bf16 v[128:131], v[166:169], v[190:193], v[128:131]
	v_mfma_f32_16x16x32_bf16 v[116:119], v[156:159], v[198:201], v[116:119]
	v_mfma_f32_16x16x32_bf16 v[112:115], v[166:169], v[198:201], v[112:115]
	v_mfma_f32_16x16x32_bf16 v[100:103], v[156:159], v[206:209], v[100:103]
	v_mfma_f32_16x16x32_bf16 v[96:99], v[166:169], v[206:209], v[96:99]
	v_mfma_f32_16x16x32_bf16 v[84:87], v[156:159], v[214:217], v[84:87]
	v_mfma_f32_16x16x32_bf16 v[80:83], v[166:169], v[214:217], v[80:83]
	s_setprio 0
	s_setprio 1
	v_mfma_f32_16x16x32_bf16 v[124:127], v[170:173], v[186:189], v[124:127]
	v_mfma_f32_16x16x32_bf16 v[120:123], v[178:181], v[186:189], v[120:123]
	v_mfma_f32_16x16x32_bf16 v[108:111], v[170:173], v[194:197], v[108:111]
	v_mfma_f32_16x16x32_bf16 v[104:107], v[178:181], v[194:197], v[104:107]
	v_mfma_f32_16x16x32_bf16 v[92:95], v[170:173], v[202:205], v[92:95]
	v_mfma_f32_16x16x32_bf16 v[88:91], v[178:181], v[202:205], v[88:91]
	v_mfma_f32_16x16x32_bf16 v[76:79], v[170:173], v[210:213], v[76:79]
	v_mfma_f32_16x16x32_bf16 v[72:75], v[178:181], v[210:213], v[72:75]
	v_mfma_f32_16x16x32_bf16 v[124:127], v[174:177], v[190:193], v[124:127]
	v_mfma_f32_16x16x32_bf16 v[120:123], v[182:185], v[190:193], v[120:123]
	v_mfma_f32_16x16x32_bf16 v[108:111], v[174:177], v[198:201], v[108:111]
	v_mfma_f32_16x16x32_bf16 v[104:107], v[182:185], v[198:201], v[104:107]
	v_mfma_f32_16x16x32_bf16 v[92:95], v[174:177], v[206:209], v[92:95]
	v_mfma_f32_16x16x32_bf16 v[88:91], v[182:185], v[206:209], v[88:91]
	v_mfma_f32_16x16x32_bf16 v[76:79], v[174:177], v[214:217], v[76:79]
	v_mfma_f32_16x16x32_bf16 v[72:75], v[182:185], v[214:217], v[72:75]
	s_setprio 0
	s_barrier
	s_add_i32 s13, s13, s31
	s_mov_b32 m0, s13
	ds_read_b128 v[186:189], v161 offset:16384
	ds_read_b128 v[190:193], v161 offset:17408
	ds_read_b128 v[194:197], v161 offset:18432
	ds_read_b128 v[198:201], v161 offset:19456
	ds_read_b128 v[202:205], v161 offset:20480
	ds_read_b128 v[206:209], v161 offset:21504
	ds_read_b128 v[210:213], v161 offset:22528
	ds_read_b128 v[214:217], v161 offset:23552
	global_load_lds_dwordx4 v140, s[24:25]
	s_add_i32 m0, s13, 0x2000
	s_add_u32 s68, s24, 0x4000
	s_addc_u32 s69, s25, 0
	s_add_i32 s13, s88, s31
	global_load_lds_dwordx4 v136, s[24:25]
	s_mov_b32 m0, s13
	s_nop 0
	global_load_lds_dwordx4 v140, s[68:69]
	s_add_i32 m0, s13, 0x2000
	s_nop 0
	global_load_lds_dwordx4 v136, s[68:69]
	s_mov_b32 m0, s19
	s_nop 0
	global_load_lds_dwordx4 v142, s[26:27]
	s_mov_b32 m0, s35
	s_nop 0
	global_load_lds_dwordx4 v138, s[26:27]
	s_waitcnt vmcnt(8)
	s_waitcnt lgkmcnt(0)
	v_mfma_f32_16x16x32_bf16 v[68:71], v[152:155], v[186:189], v[68:71]
	v_mfma_f32_16x16x32_bf16 v[64:67], v[162:165], v[186:189], v[64:67]
	v_mfma_f32_16x16x32_bf16 v[52:55], v[152:155], v[194:197], v[52:55]
	v_mfma_f32_16x16x32_bf16 v[48:51], v[162:165], v[194:197], v[48:51]
	s_barrier
; #define PG8_STAGE(bufoff, gbase, voff) do { _Pragma("unroll") for (int _i = 0; _i < 2; ++_i) \
;         __builtin_amdgcn_global_load_lds((const unsigned*)((const char*)(gbase) + (voff)[_i]), (PG8_LAS unsigned*)(lds + (bufoff) + ldsw + _i * 8192), 16, 0, 0); } while (0)
; #define PG8_LDA(dst, b, h) do { _Pragma("unroll") for (int m = 0; m < 4; ++m) _Pragma("unroll") for (int k = 0; k < 2; ++k) dst[m][k] = *(const PG8_LAS bf16x8*)(lds + PG8_SA(b, h) + aoff + m * 2048 + k * 1024); } while (0)
; #define PG8_LDB(dst, b, h) do { _Pragma("unroll") for (int n = 0; n < 2; ++n) _Pragma("unroll") for (int k = 0; k < 2; ++k) dst[n][k] = *(const PG8_LAS bf16x8*)(lds + PG8_SB(b, h) + boff + n * 2048 + k * 1024); } while (0)
; #define PG8_MMA(ai, bj, At, Bt) do { __builtin_amdgcn_s_setprio(1); _Pragma("unroll") for (int m = 0; m < 4; ++m) _Pragma("unroll") for (int n = 0; n < 2; ++n) _Pragma("unroll") for (int k = 0; k < 2; ++k) \
;         acc[ai][bj][m][n] = __builtin_amdgcn_mfma_f32_16x16x32_bf16(Bt[n][k], At[m][k], acc[ai][bj][m][n], 0, 0, 0); __builtin_amdgcn_s_setprio(0); } while (0)
; #define PG8_WAIT_V(n) asm volatile("s_waitcnt vmcnt(" #n ")" ::: "memory")
; #define PG8_WAIT_L(n) asm volatile("s_waitcnt lgkmcnt(" #n ")" ::: "memory")
; #define PG8_BAR __builtin_amdgcn_s_barrier()
; #define PG8_SCHED __builtin_amdgcn_sched_barrier(0)
; template <class Epi, class Sched, bool ALIGN_EPI = false, bool SP2 = false, bool ABLK = false, bool BBLK = false>
; __device__ __forceinline__ void gemm_phase(PG8_LAS unsigned char* lds, const Gemm g, const Sched& S, const Epi& E) {
;     ...
;             PG8_WAIT_V(8); PG8_WAIT_L(0); PG8_BAR; PG8_MMA(1, 0, At, B0); PG8_MMA(1, 1, At, B1); PG8_BAR; PG8_SCHED;
;             PG8_LDB(B0, 1, 0); PG8_LDB(B1, 1, 1); PG8_SCHED; PG8_LDA(At, 1, 0); PG8_STAGE(PG8_SA(0, 1), a2 + hstepA, voffA);
;             PG8_WAIT_V(8); PG8_WAIT_L(0); PG8_BAR; PG8_MMA(0, 0, At, B0); PG8_MMA(0, 1, At, B1); PG8_BAR; PG8_SCHED;
	s_setprio 1
	v_mfma_f32_16x16x32_bf16 v[32:35], v[152:155], v[202:205], v[32:35]
	v_mfma_f32_16x16x32_bf16 v[28:31], v[162:165], v[202:205], v[28:31]
	v_mfma_f32_16x16x32_bf16 v[16:19], v[152:155], v[210:213], v[16:19]
	v_mfma_f32_16x16x32_bf16 v[12:15], v[162:165], v[210:213], v[12:15]
	v_mfma_f32_16x16x32_bf16 v[68:71], v[156:159], v[190:193], v[68:71]
	v_mfma_f32_16x16x32_bf16 v[64:67], v[166:169], v[190:193], v[64:67]
	v_mfma_f32_16x16x32_bf16 v[52:55], v[156:159], v[198:201], v[52:55]
	v_mfma_f32_16x16x32_bf16 v[48:51], v[166:169], v[198:201], v[48:51]
	v_mfma_f32_16x16x32_bf16 v[32:35], v[156:159], v[206:209], v[32:35]
	v_mfma_f32_16x16x32_bf16 v[28:31], v[166:169], v[206:209], v[28:31]
	v_mfma_f32_16x16x32_bf16 v[16:19], v[156:159], v[214:217], v[16:19]
	v_mfma_f32_16x16x32_bf16 v[12:15], v[166:169], v[214:217], v[12:15]
	s_setprio 0
	s_setprio 1
	v_mfma_f32_16x16x32_bf16 v[60:63], v[170:173], v[186:189], v[60:63]
	v_mfma_f32_16x16x32_bf16 v[56:59], v[178:181], v[186:189], v[56:59]
	v_mfma_f32_16x16x32_bf16 v[44:47], v[170:173], v[194:197], v[44:47]
	v_mfma_f32_16x16x32_bf16 v[40:43], v[178:181], v[194:197], v[40:43]
	v_mfma_f32_16x16x32_bf16 v[24:27], v[170:173], v[202:205], v[24:27]
	v_mfma_f32_16x16x32_bf16 v[20:23], v[178:181], v[202:205], v[20:23]
	v_mfma_f32_16x16x32_bf16 v[8:11], v[170:173], v[210:213], v[8:11]
	v_mfma_f32_16x16x32_bf16 v[4:7], v[178:181], v[210:213], v[4:7]
	v_mfma_f32_16x16x32_bf16 v[60:63], v[174:177], v[190:193], v[60:63]
	v_mfma_f32_16x16x32_bf16 v[56:59], v[182:185], v[190:193], v[56:59]
	v_mfma_f32_16x16x32_bf16 v[44:47], v[174:177], v[198:201], v[44:47]
	v_mfma_f32_16x16x32_bf16 v[40:43], v[182:185], v[198:201], v[40:43]
	v_mfma_f32_16x16x32_bf16 v[24:27], v[174:177], v[206:209], v[24:27]
	v_mfma_f32_16x16x32_bf16 v[20:23], v[182:185], v[206:209], v[20:23]
	v_mfma_f32_16x16x32_bf16 v[8:11], v[174:177], v[214:217], v[8:11]
	v_mfma_f32_16x16x32_bf16 v[4:7], v[182:185], v[214:217], v[4:7]
	s_setprio 0
	s_barrier
	s_add_i32 s13, 0, 0x18000
	v_add_u32_e32 v36, s13, v160
	s_add_i32 s68, 0, 0x1c000
	ds_read_b128 v[152:155], v36
	ds_read_b128 v[156:159], v36 offset:1024
	ds_read_b128 v[162:165], v36 offset:2048
	ds_read_b128 v[166:169], v36 offset:3072
	v_add_u32_e32 v36, s68, v160
	ds_read_b128 v[170:173], v36
	ds_read_b128 v[174:177], v36 offset:1024
	ds_read_b128 v[178:181], v36 offset:2048
	ds_read_b128 v[182:185], v36 offset:3072
	s_add_u32 s26, s26, 0x4000
	s_addc_u32 s27, s27, 0
	s_mov_b32 m0, s36
	ds_read_b128 v[186:189], v161 offset:32768
	ds_read_b128 v[190:193], v161 offset:33792
	ds_read_b128 v[194:197], v161 offset:34816
	ds_read_b128 v[198:201], v161 offset:35840
	ds_read_b128 v[202:205], v161 offset:36864
	ds_read_b128 v[206:209], v161 offset:37888
	ds_read_b128 v[210:213], v161 offset:38912
	ds_read_b128 v[214:217], v161 offset:39936
	global_load_lds_dwordx4 v142, s[26:27]
	s_mov_b32 m0, s37
	s_nop 0
	global_load_lds_dwordx4 v138, s[26:27]
	s_waitcnt vmcnt(8)
	s_waitcnt lgkmcnt(0)
	v_mfma_f32_16x16x32_bf16 v[132:135], v[152:155], v[186:189], v[132:135]
	v_mfma_f32_16x16x32_bf16 v[128:131], v[162:165], v[186:189], v[128:131]
	v_mfma_f32_16x16x32_bf16 v[116:119], v[152:155], v[194:197], v[116:119]
	v_mfma_f32_16x16x32_bf16 v[112:115], v[162:165], v[194:197], v[112:115]
	s_barrier
	s_setprio 1
	v_mfma_f32_16x16x32_bf16 v[100:103], v[152:155], v[202:205], v[100:103]
	v_mfma_f32_16x16x32_bf16 v[96:99], v[162:165], v[202:205], v[96:99]
	v_mfma_f32_16x16x32_bf16 v[84:87], v[152:155], v[210:213], v[84:87]
	v_mfma_f32_16x16x32_bf16 v[80:83], v[162:165], v[210:213], v[80:83]
	v_mfma_f32_16x16x32_bf16 v[132:135], v[156:159], v[190:193], v[132:135]
	v_mfma_f32_16x16x32_bf16 v[128:131], v[166:169], v[190:193], v[128:131]
	v_mfma_f32_16x16x32_bf16 v[116:119], v[156:159], v[198:201], v[116:119]
	v_mfma_f32_16x16x32_bf16 v[112:115], v[166:169], v[198:201], v[112:115]
	v_mfma_f32_16x16x32_bf16 v[100:103], v[156:159], v[206:209], v[100:103]
	v_mfma_f32_16x16x32_bf16 v[96:99], v[166:169], v[206:209], v[96:99]
	v_mfma_f32_16x16x32_bf16 v[84:87], v[156:159], v[214:217], v[84:87]
	v_mfma_f32_16x16x32_bf16 v[80:83], v[166:169], v[214:217], v[80:83]
	s_setprio 0
	s_setprio 1
	v_mfma_f32_16x16x32_bf16 v[124:127], v[170:173], v[186:189], v[124:127]
	v_mfma_f32_16x16x32_bf16 v[120:123], v[178:181], v[186:189], v[120:123]
	v_mfma_f32_16x16x32_bf16 v[108:111], v[170:173], v[194:197], v[108:111]
	v_mfma_f32_16x16x32_bf16 v[104:107], v[178:181], v[194:197], v[104:107]
	v_mfma_f32_16x16x32_bf16 v[92:95], v[170:173], v[202:205], v[92:95]
	v_mfma_f32_16x16x32_bf16 v[88:91], v[178:181], v[202:205], v[88:91]
	v_mfma_f32_16x16x32_bf16 v[76:79], v[170:173], v[210:213], v[76:79]
	v_mfma_f32_16x16x32_bf16 v[72:75], v[178:181], v[210:213], v[72:75]
	v_mfma_f32_16x16x32_bf16 v[124:127], v[174:177], v[190:193], v[124:127]
	v_mfma_f32_16x16x32_bf16 v[120:123], v[182:185], v[190:193], v[120:123]
	v_mfma_f32_16x16x32_bf16 v[108:111], v[174:177], v[198:201], v[108:111]
	v_mfma_f32_16x16x32_bf16 v[104:107], v[182:185], v[198:201], v[104:107]
	v_mfma_f32_16x16x32_bf16 v[92:95], v[174:177], v[206:209], v[92:95]
	v_mfma_f32_16x16x32_bf16 v[88:91], v[182:185], v[206:209], v[88:91]
	v_mfma_f32_16x16x32_bf16 v[76:79], v[174:177], v[214:217], v[76:79]
	v_mfma_f32_16x16x32_bf16 v[72:75], v[182:185], v[214:217], v[72:75]
	s_setprio 0
	s_barrier
; #define PG8_STAGE(bufoff, gbase, voff) do { _Pragma("unroll") for (int _i = 0; _i < 2; ++_i) \
;         __builtin_amdgcn_global_load_lds((const unsigned*)((const char*)(gbase) + (voff)[_i]), (PG8_LAS unsigned*)(lds + (bufoff) + ldsw + _i * 8192), 16, 0, 0); } while (0)
; #define PG8_LDA(dst, b, h) do { _Pragma("unroll") for (int m = 0; m < 4; ++m) _Pragma("unroll") for (int k = 0; k < 2; ++k) dst[m][k] = *(const PG8_LAS bf16x8*)(lds + PG8_SA(b, h) + aoff + m * 2048 + k * 1024); } while (0)
; #define PG8_MMA(ai, bj, At, Bt) do { __builtin_amdgcn_s_setprio(1); _Pragma("unroll") for (int m = 0; m < 4; ++m) _Pragma("unroll") for (int n = 0; n < 2; ++n) _Pragma("unroll") for (int k = 0; k < 2; ++k) \
;         acc[ai][bj][m][n] = __builtin_amdgcn_mfma_f32_16x16x32_bf16(Bt[n][k], At[m][k], acc[ai][bj][m][n], 0, 0, 0); __builtin_amdgcn_s_setprio(0); } while (0)
; #define PG8_WAIT_V(n) asm volatile("s_waitcnt vmcnt(" #n ")" ::: "memory")
; #define PG8_WAIT_L(n) asm volatile("s_waitcnt lgkmcnt(" #n ")" ::: "memory")
; #define PG8_BAR __builtin_amdgcn_s_barrier()
; #define PG8_SCHED __builtin_amdgcn_sched_barrier(0)
; template <class Epi, class Sched, bool ALIGN_EPI = false, bool SP2 = false, bool ABLK = false, bool BBLK = false>
; __device__ __forceinline__ void gemm_phase(PG8_LAS unsigned char* lds, const Gemm g, const Sched& S, const Epi& E) {
;     ...
;             PG8_LDA(At, 1, 1); PG8_STAGE(PG8_SB(1, 0), b3, voffB); PG8_STAGE(PG8_SB(1, 1), b3 + hstepB, voffB); PG8_STAGE(PG8_SA(1, 0), a3, voffA);
;             PG8_WAIT_V(8); PG8_WAIT_L(0); PG8_BAR; PG8_MMA(1, 0, At, B0); PG8_MMA(1, 1, At, B1); PG8_BAR; PG8_SCHED;
	s_add_u32 s26, s24, 0x8000
	s_addc_u32 s27, s25, 0
	s_add_i32 s13, s13, s31
	s_mov_b32 m0, s13
	ds_read_b128 v[186:189], v161 offset:49152
	ds_read_b128 v[190:193], v161 offset:50176
	ds_read_b128 v[194:197], v161 offset:51200
	ds_read_b128 v[198:201], v161 offset:52224
	ds_read_b128 v[202:205], v161 offset:53248
	ds_read_b128 v[206:209], v161 offset:54272
	ds_read_b128 v[210:213], v161 offset:55296
	ds_read_b128 v[214:217], v161 offset:56320
	global_load_lds_dwordx4 v140, s[26:27]
	s_add_i32 m0, s13, 0x2000
	s_add_u32 s24, s24, 0xc000
	s_addc_u32 s25, s25, 0
	s_add_i32 s13, s68, s31
	global_load_lds_dwordx4 v136, s[26:27]
	s_mov_b32 m0, s13
	s_nop 0
	global_load_lds_dwordx4 v140, s[24:25]
	s_add_i32 m0, s13, 0x2000
	s_nop 0
	global_load_lds_dwordx4 v136, s[24:25]
	s_mov_b32 m0, s62
	s_nop 0
	global_load_lds_dwordx4 v142, s[22:23]
	s_mov_b32 m0, s63
	s_nop 0
	global_load_lds_dwordx4 v138, s[22:23]
	s_waitcnt vmcnt(8)
	s_waitcnt lgkmcnt(0)
	v_mfma_f32_16x16x32_bf16 v[68:71], v[152:155], v[186:189], v[68:71]
	v_mfma_f32_16x16x32_bf16 v[64:67], v[162:165], v[186:189], v[64:67]
	v_mfma_f32_16x16x32_bf16 v[52:55], v[152:155], v[194:197], v[52:55]
	v_mfma_f32_16x16x32_bf16 v[48:51], v[162:165], v[194:197], v[48:51]
	s_barrier
	s_setprio 1
	v_mfma_f32_16x16x32_bf16 v[32:35], v[152:155], v[202:205], v[32:35]
	v_mfma_f32_16x16x32_bf16 v[28:31], v[162:165], v[202:205], v[28:31]
	v_mfma_f32_16x16x32_bf16 v[16:19], v[152:155], v[210:213], v[16:19]
	v_mfma_f32_16x16x32_bf16 v[12:15], v[162:165], v[210:213], v[12:15]
	v_mfma_f32_16x16x32_bf16 v[68:71], v[156:159], v[190:193], v[68:71]
	v_mfma_f32_16x16x32_bf16 v[64:67], v[166:169], v[190:193], v[64:67]
	v_mfma_f32_16x16x32_bf16 v[52:55], v[156:159], v[198:201], v[52:55]
	v_mfma_f32_16x16x32_bf16 v[48:51], v[166:169], v[198:201], v[48:51]
	v_mfma_f32_16x16x32_bf16 v[32:35], v[156:159], v[206:209], v[32:35]
	v_mfma_f32_16x16x32_bf16 v[28:31], v[166:169], v[206:209], v[28:31]
	v_mfma_f32_16x16x32_bf16 v[16:19], v[156:159], v[214:217], v[16:19]
	v_mfma_f32_16x16x32_bf16 v[12:15], v[166:169], v[214:217], v[12:15]
	s_setprio 0
	s_setprio 1
	v_mfma_f32_16x16x32_bf16 v[60:63], v[170:173], v[186:189], v[60:63]
	v_mfma_f32_16x16x32_bf16 v[56:59], v[178:181], v[186:189], v[56:59]
	v_mfma_f32_16x16x32_bf16 v[44:47], v[170:173], v[194:197], v[44:47]
	v_mfma_f32_16x16x32_bf16 v[40:43], v[178:181], v[194:197], v[40:43]
	v_mfma_f32_16x16x32_bf16 v[24:27], v[170:173], v[202:205], v[24:27]
	v_mfma_f32_16x16x32_bf16 v[20:23], v[178:181], v[202:205], v[20:23]
	v_mfma_f32_16x16x32_bf16 v[8:11], v[170:173], v[210:213], v[8:11]
	v_mfma_f32_16x16x32_bf16 v[4:7], v[178:181], v[210:213], v[4:7]
	v_mfma_f32_16x16x32_bf16 v[60:63], v[174:177], v[190:193], v[60:63]
	v_mfma_f32_16x16x32_bf16 v[56:59], v[182:185], v[190:193], v[56:59]
	v_mfma_f32_16x16x32_bf16 v[44:47], v[174:177], v[198:201], v[44:47]
	v_mfma_f32_16x16x32_bf16 v[40:43], v[182:185], v[198:201], v[40:43]
	v_mfma_f32_16x16x32_bf16 v[24:27], v[174:177], v[206:209], v[24:27]
	v_mfma_f32_16x16x32_bf16 v[20:23], v[182:185], v[206:209], v[20:23]
	v_mfma_f32_16x16x32_bf16 v[8:11], v[174:177], v[214:217], v[8:11]
	v_mfma_f32_16x16x32_bf16 v[4:7], v[182:185], v[214:217], v[4:7]
	s_setprio 0
	s_barrier
	s_add_i32 vcc_hi, vcc_hi, 2
	s_add_u32 s20, s20, 0x10000
	s_addc_u32 s21, s21, 0
	s_add_u32 s77, s77, 0x10000
	s_addc_u32 vcc_lo, vcc_lo, 0
	s_cmp_gt_u32 vcc_hi, 29
	s_cbranch_scc0 .LBB0_185
	s_and_b64 vcc, exec, s[4:5]
	s_cbranch_vccz .LBB0_188
	s_barrier

; #define PG8_STAGE(bufoff, gbase, voff) do { _Pragma("unroll") for (int _i = 0; _i < 2; ++_i) \
;         __builtin_amdgcn_global_load_lds((const unsigned*)((const char*)(gbase) + (voff)[_i]), (PG8_LAS unsigned*)(lds + (bufoff) + ldsw + _i * 8192), 16, 0, 0); } while (0)
; #define PG8_LDA(dst, b, h) do { _Pragma("unroll") for (int m = 0; m < 4; ++m) _Pragma("unroll") for (int k = 0; k < 2; ++k) dst[m][k] = *(const PG8_LAS bf16x8*)(lds + PG8_SA(b, h) + aoff + m * 2048 + k * 1024); } while (0)
; #define PG8_LDB(dst, b, h) do { _Pragma("unroll") for (int n = 0; n < 2; ++n) _Pragma("unroll") for (int k = 0; k < 2; ++k) dst[n][k] = *(const PG8_LAS bf16x8*)(lds + PG8_SB(b, h) + boff + n * 2048 + k * 1024); } while (0)
; #define PG8_MMA(ai, bj, At, Bt) do { __builtin_amdgcn_s_setprio(1); _Pragma("unroll") for (int m = 0; m < 4; ++m) _Pragma("unroll") for (int n = 0; n < 2; ++n) _Pragma("unroll") for (int k = 0; k < 2; ++k) \
;         acc[ai][bj][m][n] = __builtin_amdgcn_mfma_f32_16x16x32_bf16(Bt[n][k], At[m][k], acc[ai][bj][m][n], 0, 0, 0); __builtin_amdgcn_s_setprio(0); } while (0)
; #define PG8_WAIT_V(n) asm volatile("s_waitcnt vmcnt(" #n ")" ::: "memory")
; #define PG8_WAIT_L(n) asm volatile("s_waitcnt lgkmcnt(" #n ")" ::: "memory")
; #define PG8_BAR __builtin_amdgcn_s_barrier()
; #define PG8_SCHED __builtin_amdgcn_sched_barrier(0)
; template <class Epi, class Sched, bool ALIGN_EPI = false, bool SP2 = false, bool ABLK = false, bool BBLK = false>
; __device__ __forceinline__ void gemm_phase(PG8_LAS unsigned char* lds, const Gemm g, const Sched& S, const Epi& E) {
;     ...
;             PG8_LDB(B0, 0, 0); PG8_LDB(B1, 0, 1); PG8_SCHED; PG8_LDA(At, 0, 0); PG8_STAGE(PG8_SA(1, 1), a1 + hstepA, voffA);
;             PG8_WAIT_V(8); PG8_WAIT_L(0); PG8_BAR; PG8_MMA(0, 0, At, B0); PG8_MMA(0, 1, At, B1); PG8_BAR; PG8_SCHED;
;             PG8_LDA(At, 0, 1); PG8_STAGE(PG8_SB(0, 0), b2, voffB); PG8_STAGE(PG8_SB(0, 1), b2 + hstepB, voffB); PG8_STAGE(PG8_SA(0, 0), a2, voffA);
;             PG8_WAIT_V(8); PG8_WAIT_L(0); PG8_BAR; PG8_MMA(1, 0, At, B0); PG8_MMA(1, 1, At, B1); PG8_BAR; PG8_SCHED;
.LBB0_439:
	s_add_u32 s16, s10, 0x4000
	s_addc_u32 s17, s11, 0
	s_cmpk_eq_i32 s13, 0x54
	s_cselect_b32 s20, s0, s16
	s_cselect_b32 s21, s1, s17
	s_cselect_b32 s18, s8, vcc_lo
	s_cselect_b32 s19, s9, vcc_hi
	s_add_u32 s16, s20, 0x8000
	s_addc_u32 s17, s21, 0
	s_add_i32 s68, 0, 0x10000
	v_add_u32_e32 v36, s68, v148
	s_add_i32 s88, 0, 0x14000
	ds_read_b128 v[152:155], v36
	ds_read_b128 v[156:159], v36 offset:1024
	ds_read_b128 v[160:163], v36 offset:2048
	ds_read_b128 v[164:167], v36 offset:3072
	v_add_u32_e32 v36, s88, v148
	ds_read_b128 v[168:171], v36
	ds_read_b128 v[172:175], v36 offset:1024
	ds_read_b128 v[176:179], v36 offset:2048
	ds_read_b128 v[180:183], v36 offset:3072
	s_add_i32 m0, s27, 0xc000
	ds_read_b128 v[184:187], v150
	ds_read_b128 v[188:191], v150 offset:1024
	ds_read_b128 v[192:195], v150 offset:2048
	ds_read_b128 v[196:199], v150 offset:3072
	ds_read_b128 v[200:203], v150 offset:4096
	ds_read_b128 v[204:207], v150 offset:5120
	ds_read_b128 v[208:211], v150 offset:6144
	ds_read_b128 v[212:215], v150 offset:7168
	global_load_lds_dwordx4 v144, s[10:11]
	s_add_i32 m0, s27, 0xe000
	s_nop 0
	global_load_lds_dwordx4 v146, s[10:11]
	s_waitcnt vmcnt(8)
	s_waitcnt lgkmcnt(0)
	v_mfma_f32_16x16x32_bf16 v[132:135], v[152:155], v[184:187], v[132:135]
	v_mfma_f32_16x16x32_bf16 v[128:131], v[160:163], v[184:187], v[128:131]
	v_mfma_f32_16x16x32_bf16 v[124:127], v[152:155], v[192:195], v[124:127]
	v_mfma_f32_16x16x32_bf16 v[120:123], v[160:163], v[192:195], v[120:123]
	s_barrier
	s_setprio 1
	v_mfma_f32_16x16x32_bf16 v[108:111], v[152:155], v[200:203], v[108:111]
	v_mfma_f32_16x16x32_bf16 v[104:107], v[160:163], v[200:203], v[104:107]
	v_mfma_f32_16x16x32_bf16 v[92:95], v[152:155], v[208:211], v[92:95]
	v_mfma_f32_16x16x32_bf16 v[88:91], v[160:163], v[208:211], v[88:91]
	v_mfma_f32_16x16x32_bf16 v[132:135], v[156:159], v[188:191], v[132:135]
	v_mfma_f32_16x16x32_bf16 v[128:131], v[164:167], v[188:191], v[128:131]
	v_mfma_f32_16x16x32_bf16 v[124:127], v[156:159], v[196:199], v[124:127]
	v_mfma_f32_16x16x32_bf16 v[120:123], v[164:167], v[196:199], v[120:123]
	v_mfma_f32_16x16x32_bf16 v[108:111], v[156:159], v[204:207], v[108:111]
	v_mfma_f32_16x16x32_bf16 v[104:107], v[164:167], v[204:207], v[104:107]
	v_mfma_f32_16x16x32_bf16 v[92:95], v[156:159], v[212:215], v[92:95]
	v_mfma_f32_16x16x32_bf16 v[88:91], v[164:167], v[212:215], v[88:91]
	s_setprio 0
	s_setprio 1
	v_mfma_f32_16x16x32_bf16 v[116:119], v[168:171], v[184:187], v[116:119]
	v_mfma_f32_16x16x32_bf16 v[112:115], v[176:179], v[184:187], v[112:115]
	v_mfma_f32_16x16x32_bf16 v[100:103], v[168:171], v[192:195], v[100:103]
	v_mfma_f32_16x16x32_bf16 v[96:99], v[176:179], v[192:195], v[96:99]
	v_mfma_f32_16x16x32_bf16 v[84:87], v[168:171], v[200:203], v[84:87]
	v_mfma_f32_16x16x32_bf16 v[80:83], v[176:179], v[200:203], v[80:83]
	v_mfma_f32_16x16x32_bf16 v[76:79], v[168:171], v[208:211], v[76:79]
	v_mfma_f32_16x16x32_bf16 v[72:75], v[176:179], v[208:211], v[72:75]
	v_mfma_f32_16x16x32_bf16 v[116:119], v[172:175], v[188:191], v[116:119]
	v_mfma_f32_16x16x32_bf16 v[112:115], v[180:183], v[188:191], v[112:115]
	v_mfma_f32_16x16x32_bf16 v[100:103], v[172:175], v[196:199], v[100:103]
	v_mfma_f32_16x16x32_bf16 v[96:99], v[180:183], v[196:199], v[96:99]
	v_mfma_f32_16x16x32_bf16 v[84:87], v[172:175], v[204:207], v[84:87]
	v_mfma_f32_16x16x32_bf16 v[80:83], v[180:183], v[204:207], v[80:83]
	v_mfma_f32_16x16x32_bf16 v[76:79], v[172:175], v[212:215], v[76:79]
	v_mfma_f32_16x16x32_bf16 v[72:75], v[180:183], v[212:215], v[72:75]
	s_setprio 0
	s_barrier
	s_add_i32 s68, s68, s24
	s_mov_b32 m0, s68
	ds_read_b128 v[184:187], v150 offset:16384
	ds_read_b128 v[188:191], v150 offset:17408
	ds_read_b128 v[192:195], v150 offset:18432
	ds_read_b128 v[196:199], v150 offset:19456
	ds_read_b128 v[200:203], v150 offset:20480
	ds_read_b128 v[204:207], v150 offset:21504
	ds_read_b128 v[208:211], v150 offset:22528
	ds_read_b128 v[212:215], v150 offset:23552
	global_load_lds_dwordx4 v138, s[18:19]
	s_add_i32 m0, s68, 0x2000
	s_add_u32 s68, s18, 0x4000
	s_addc_u32 s69, s19, 0
	s_add_i32 s88, s88, s24
	global_load_lds_dwordx4 v142, s[18:19]
	s_mov_b32 m0, s88
	s_nop 0
	global_load_lds_dwordx4 v138, s[68:69]
	s_add_i32 m0, s88, 0x2000
	s_nop 0
	global_load_lds_dwordx4 v142, s[68:69]
	s_mov_b32 m0, s27
	s_nop 0
	global_load_lds_dwordx4 v136, s[20:21]
	s_mov_b32 m0, s28
	s_nop 0
	global_load_lds_dwordx4 v140, s[20:21]
	s_waitcnt vmcnt(8)
	s_waitcnt lgkmcnt(0)
	v_mfma_f32_16x16x32_bf16 v[68:71], v[152:155], v[184:187], v[68:71]
	v_mfma_f32_16x16x32_bf16 v[64:67], v[160:163], v[184:187], v[64:67]
	v_mfma_f32_16x16x32_bf16 v[60:63], v[152:155], v[192:195], v[60:63]
	v_mfma_f32_16x16x32_bf16 v[56:59], v[160:163], v[192:195], v[56:59]
	s_barrier
; #define PG8_STAGE(bufoff, gbase, voff) do { _Pragma("unroll") for (int _i = 0; _i < 2; ++_i) \
;         __builtin_amdgcn_global_load_lds((const unsigned*)((const char*)(gbase) + (voff)[_i]), (PG8_LAS unsigned*)(lds + (bufoff) + ldsw + _i * 8192), 16, 0, 0); } while (0)
; #define PG8_LDA(dst, b, h) do { _Pragma("unroll") for (int m = 0; m < 4; ++m) _Pragma("unroll") for (int k = 0; k < 2; ++k) dst[m][k] = *(const PG8_LAS bf16x8*)(lds + PG8_SA(b, h) + aoff + m * 2048 + k * 1024); } while (0)
; #define PG8_LDB(dst, b, h) do { _Pragma("unroll") for (int n = 0; n < 2; ++n) _Pragma("unroll") for (int k = 0; k < 2; ++k) dst[n][k] = *(const PG8_LAS bf16x8*)(lds + PG8_SB(b, h) + boff + n * 2048 + k * 1024); } while (0)
; #define PG8_MMA(ai, bj, At, Bt) do { __builtin_amdgcn_s_setprio(1); _Pragma("unroll") for (int m = 0; m < 4; ++m) _Pragma("unroll") for (int n = 0; n < 2; ++n) _Pragma("unroll") for (int k = 0; k < 2; ++k) \
;         acc[ai][bj][m][n] = __builtin_amdgcn_mfma_f32_16x16x32_bf16(Bt[n][k], At[m][k], acc[ai][bj][m][n], 0, 0, 0); __builtin_amdgcn_s_setprio(0); } while (0)
; #define PG8_WAIT_V(n) asm volatile("s_waitcnt vmcnt(" #n ")" ::: "memory")
; #define PG8_WAIT_L(n) asm volatile("s_waitcnt lgkmcnt(" #n ")" ::: "memory")
; #define PG8_BAR __builtin_amdgcn_s_barrier()
; #define PG8_SCHED __builtin_amdgcn_sched_barrier(0)
; template <class Epi, class Sched, bool ALIGN_EPI = false, bool SP2 = false, bool ABLK = false, bool BBLK = false>
; __device__ __forceinline__ void gemm_phase(PG8_LAS unsigned char* lds, const Gemm g, const Sched& S, const Epi& E) {
;     ...
;             PG8_WAIT_V(8); PG8_WAIT_L(0); PG8_BAR; PG8_MMA(1, 0, At, B0); PG8_MMA(1, 1, At, B1); PG8_BAR; PG8_SCHED;
;             PG8_LDB(B0, 1, 0); PG8_LDB(B1, 1, 1); PG8_SCHED; PG8_LDA(At, 1, 0); PG8_STAGE(PG8_SA(0, 1), a2 + hstepA, voffA);
;             PG8_WAIT_V(8); PG8_WAIT_L(0); PG8_BAR; PG8_MMA(0, 0, At, B0); PG8_MMA(0, 1, At, B1); PG8_BAR; PG8_SCHED;
	s_setprio 1
	v_mfma_f32_16x16x32_bf16 v[44:47], v[152:155], v[200:203], v[44:47]
	v_mfma_f32_16x16x32_bf16 v[40:43], v[160:163], v[200:203], v[40:43]
	v_mfma_f32_16x16x32_bf16 v[24:27], v[152:155], v[208:211], v[24:27]
	v_mfma_f32_16x16x32_bf16 v[20:23], v[160:163], v[208:211], v[20:23]
	v_mfma_f32_16x16x32_bf16 v[68:71], v[156:159], v[188:191], v[68:71]
	v_mfma_f32_16x16x32_bf16 v[64:67], v[164:167], v[188:191], v[64:67]
	v_mfma_f32_16x16x32_bf16 v[60:63], v[156:159], v[196:199], v[60:63]
	v_mfma_f32_16x16x32_bf16 v[56:59], v[164:167], v[196:199], v[56:59]
	v_mfma_f32_16x16x32_bf16 v[44:47], v[156:159], v[204:207], v[44:47]
	v_mfma_f32_16x16x32_bf16 v[40:43], v[164:167], v[204:207], v[40:43]
	v_mfma_f32_16x16x32_bf16 v[24:27], v[156:159], v[212:215], v[24:27]
	v_mfma_f32_16x16x32_bf16 v[20:23], v[164:167], v[212:215], v[20:23]
	s_setprio 0
	s_setprio 1
	v_mfma_f32_16x16x32_bf16 v[52:55], v[168:171], v[184:187], v[52:55]
	v_mfma_f32_16x16x32_bf16 v[48:51], v[176:179], v[184:187], v[48:51]
	v_mfma_f32_16x16x32_bf16 v[32:35], v[168:171], v[192:195], v[32:35]
	v_mfma_f32_16x16x32_bf16 v[28:31], v[176:179], v[192:195], v[28:31]
	v_mfma_f32_16x16x32_bf16 v[16:19], v[168:171], v[200:203], v[16:19]
	v_mfma_f32_16x16x32_bf16 v[12:15], v[176:179], v[200:203], v[12:15]
	v_mfma_f32_16x16x32_bf16 v[8:11], v[168:171], v[208:211], v[8:11]
	v_mfma_f32_16x16x32_bf16 v[4:7], v[176:179], v[208:211], v[4:7]
	v_mfma_f32_16x16x32_bf16 v[52:55], v[172:175], v[188:191], v[52:55]
	v_mfma_f32_16x16x32_bf16 v[48:51], v[180:183], v[188:191], v[48:51]
	v_mfma_f32_16x16x32_bf16 v[32:35], v[172:175], v[196:199], v[32:35]
	v_mfma_f32_16x16x32_bf16 v[28:31], v[180:183], v[196:199], v[28:31]
	v_mfma_f32_16x16x32_bf16 v[16:19], v[172:175], v[204:207], v[16:19]
	v_mfma_f32_16x16x32_bf16 v[12:15], v[180:183], v[204:207], v[12:15]
	v_mfma_f32_16x16x32_bf16 v[8:11], v[172:175], v[212:215], v[8:11]
	v_mfma_f32_16x16x32_bf16 v[4:7], v[180:183], v[212:215], v[4:7]
	s_setprio 0
	s_barrier
	s_add_i32 s68, 0, 0x18000
	v_add_u32_e32 v36, s68, v148
	s_add_i32 s69, 0, 0x1c000
	ds_read_b128 v[152:155], v36
	ds_read_b128 v[156:159], v36 offset:1024
	ds_read_b128 v[160:163], v36 offset:2048
	ds_read_b128 v[164:167], v36 offset:3072
	v_add_u32_e32 v36, s69, v148
	ds_read_b128 v[168:171], v36
	ds_read_b128 v[172:175], v36 offset:1024
	ds_read_b128 v[176:179], v36 offset:2048
	ds_read_b128 v[180:183], v36 offset:3072
	s_add_u32 s20, s20, 0x4000
	s_addc_u32 s21, s21, 0
	s_mov_b32 m0, s29
	ds_read_b128 v[184:187], v150 offset:32768
	ds_read_b128 v[188:191], v150 offset:33792
	ds_read_b128 v[192:195], v150 offset:34816
	ds_read_b128 v[196:199], v150 offset:35840
	ds_read_b128 v[200:203], v150 offset:36864
	ds_read_b128 v[204:207], v150 offset:37888
	ds_read_b128 v[208:211], v150 offset:38912
	ds_read_b128 v[212:215], v150 offset:39936
	global_load_lds_dwordx4 v136, s[20:21]
	s_mov_b32 m0, s30
	s_nop 0
	global_load_lds_dwordx4 v140, s[20:21]
	s_waitcnt vmcnt(8)
	s_waitcnt lgkmcnt(0)
	v_mfma_f32_16x16x32_bf16 v[132:135], v[152:155], v[184:187], v[132:135]
	v_mfma_f32_16x16x32_bf16 v[128:131], v[160:163], v[184:187], v[128:131]
	v_mfma_f32_16x16x32_bf16 v[124:127], v[152:155], v[192:195], v[124:127]
	v_mfma_f32_16x16x32_bf16 v[120:123], v[160:163], v[192:195], v[120:123]
	s_barrier
	s_setprio 1
	v_mfma_f32_16x16x32_bf16 v[108:111], v[152:155], v[200:203], v[108:111]
	v_mfma_f32_16x16x32_bf16 v[104:107], v[160:163], v[200:203], v[104:107]
	v_mfma_f32_16x16x32_bf16 v[92:95], v[152:155], v[208:211], v[92:95]
	v_mfma_f32_16x16x32_bf16 v[88:91], v[160:163], v[208:211], v[88:91]
	v_mfma_f32_16x16x32_bf16 v[132:135], v[156:159], v[188:191], v[132:135]
	v_mfma_f32_16x16x32_bf16 v[128:131], v[164:167], v[188:191], v[128:131]
	v_mfma_f32_16x16x32_bf16 v[124:127], v[156:159], v[196:199], v[124:127]
	v_mfma_f32_16x16x32_bf16 v[120:123], v[164:167], v[196:199], v[120:123]
	v_mfma_f32_16x16x32_bf16 v[108:111], v[156:159], v[204:207], v[108:111]
	v_mfma_f32_16x16x32_bf16 v[104:107], v[164:167], v[204:207], v[104:107]
	v_mfma_f32_16x16x32_bf16 v[92:95], v[156:159], v[212:215], v[92:95]
	v_mfma_f32_16x16x32_bf16 v[88:91], v[164:167], v[212:215], v[88:91]
	s_setprio 0
	s_setprio 1
	v_mfma_f32_16x16x32_bf16 v[116:119], v[168:171], v[184:187], v[116:119]
	v_mfma_f32_16x16x32_bf16 v[112:115], v[176:179], v[184:187], v[112:115]
	v_mfma_f32_16x16x32_bf16 v[100:103], v[168:171], v[192:195], v[100:103]
	v_mfma_f32_16x16x32_bf16 v[96:99], v[176:179], v[192:195], v[96:99]
	v_mfma_f32_16x16x32_bf16 v[84:87], v[168:171], v[200:203], v[84:87]
	v_mfma_f32_16x16x32_bf16 v[80:83], v[176:179], v[200:203], v[80:83]
	v_mfma_f32_16x16x32_bf16 v[76:79], v[168:171], v[208:211], v[76:79]
	v_mfma_f32_16x16x32_bf16 v[72:75], v[176:179], v[208:211], v[72:75]
	v_mfma_f32_16x16x32_bf16 v[116:119], v[172:175], v[188:191], v[116:119]
	v_mfma_f32_16x16x32_bf16 v[112:115], v[180:183], v[188:191], v[112:115]
	v_mfma_f32_16x16x32_bf16 v[100:103], v[172:175], v[196:199], v[100:103]
	v_mfma_f32_16x16x32_bf16 v[96:99], v[180:183], v[196:199], v[96:99]
	v_mfma_f32_16x16x32_bf16 v[84:87], v[172:175], v[204:207], v[84:87]
	v_mfma_f32_16x16x32_bf16 v[80:83], v[180:183], v[204:207], v[80:83]
	v_mfma_f32_16x16x32_bf16 v[76:79], v[172:175], v[212:215], v[76:79]
	v_mfma_f32_16x16x32_bf16 v[72:75], v[180:183], v[212:215], v[72:75]
	s_setprio 0
	s_barrier
; #define PG8_STAGE(bufoff, gbase, voff) do { _Pragma("unroll") for (int _i = 0; _i < 2; ++_i) \
;         __builtin_amdgcn_global_load_lds((const unsigned*)((const char*)(gbase) + (voff)[_i]), (PG8_LAS unsigned*)(lds + (bufoff) + ldsw + _i * 8192), 16, 0, 0); } while (0)
; #define PG8_LDA(dst, b, h) do { _Pragma("unroll") for (int m = 0; m < 4; ++m) _Pragma("unroll") for (int k = 0; k < 2; ++k) dst[m][k] = *(const PG8_LAS bf16x8*)(lds + PG8_SA(b, h) + aoff + m * 2048 + k * 1024); } while (0)
; #define PG8_MMA(ai, bj, At, Bt) do { __builtin_amdgcn_s_setprio(1); _Pragma("unroll") for (int m = 0; m < 4; ++m) _Pragma("unroll") for (int n = 0; n < 2; ++n) _Pragma("unroll") for (int k = 0; k < 2; ++k) \
;         acc[ai][bj][m][n] = __builtin_amdgcn_mfma_f32_16x16x32_bf16(Bt[n][k], At[m][k], acc[ai][bj][m][n], 0, 0, 0); __builtin_amdgcn_s_setprio(0); } while (0)
; #define PG8_WAIT_V(n) asm volatile("s_waitcnt vmcnt(" #n ")" ::: "memory")
; #define PG8_WAIT_L(n) asm volatile("s_waitcnt lgkmcnt(" #n ")" ::: "memory")
; #define PG8_BAR __builtin_amdgcn_s_barrier()
; #define PG8_SCHED __builtin_amdgcn_sched_barrier(0)
; template <class Epi, class Sched, bool ALIGN_EPI = false, bool SP2 = false, bool ABLK = false, bool BBLK = false>
; __device__ __forceinline__ void gemm_phase(PG8_LAS unsigned char* lds, const Gemm g, const Sched& S, const Epi& E) {
;     ...
;             PG8_LDA(At, 1, 1); PG8_STAGE(PG8_SB(1, 0), b3, voffB); PG8_STAGE(PG8_SB(1, 1), b3 + hstepB, voffB); PG8_STAGE(PG8_SA(1, 0), a3, voffA);
;             PG8_WAIT_V(8); PG8_WAIT_L(0); PG8_BAR; PG8_MMA(1, 0, At, B0); PG8_MMA(1, 1, At, B1); PG8_BAR; PG8_SCHED;
	s_add_u32 s20, s18, 0x8000
	s_addc_u32 s21, s19, 0
	s_add_i32 s68, s68, s24
	s_mov_b32 m0, s68
	ds_read_b128 v[184:187], v150 offset:49152
	ds_read_b128 v[188:191], v150 offset:50176
	ds_read_b128 v[192:195], v150 offset:51200
	ds_read_b128 v[196:199], v150 offset:52224
	ds_read_b128 v[200:203], v150 offset:53248
	ds_read_b128 v[204:207], v150 offset:54272
	ds_read_b128 v[208:211], v150 offset:55296
	ds_read_b128 v[212:215], v150 offset:56320
	global_load_lds_dwordx4 v138, s[20:21]
	s_add_i32 m0, s68, 0x2000
	s_add_u32 s18, s18, 0xc000
	s_addc_u32 s19, s19, 0
	global_load_lds_dwordx4 v142, s[20:21]
	s_add_i32 s20, s69, s24
	s_mov_b32 m0, s20
	s_nop 0
	global_load_lds_dwordx4 v138, s[18:19]
	s_add_i32 m0, s20, 0x2000
	s_nop 0
	global_load_lds_dwordx4 v142, s[18:19]
	s_mov_b32 m0, s35
	s_nop 0
	global_load_lds_dwordx4 v136, s[16:17]
	s_mov_b32 m0, s70
	s_nop 0
	global_load_lds_dwordx4 v140, s[16:17]
	s_waitcnt vmcnt(8)
	s_waitcnt lgkmcnt(0)
	v_mfma_f32_16x16x32_bf16 v[68:71], v[152:155], v[184:187], v[68:71]
	v_mfma_f32_16x16x32_bf16 v[64:67], v[160:163], v[184:187], v[64:67]
	v_mfma_f32_16x16x32_bf16 v[60:63], v[152:155], v[192:195], v[60:63]
	v_mfma_f32_16x16x32_bf16 v[56:59], v[160:163], v[192:195], v[56:59]
	s_barrier
	s_setprio 1
	v_mfma_f32_16x16x32_bf16 v[44:47], v[152:155], v[200:203], v[44:47]
	v_mfma_f32_16x16x32_bf16 v[40:43], v[160:163], v[200:203], v[40:43]
	v_mfma_f32_16x16x32_bf16 v[24:27], v[152:155], v[208:211], v[24:27]
	v_mfma_f32_16x16x32_bf16 v[20:23], v[160:163], v[208:211], v[20:23]
	v_mfma_f32_16x16x32_bf16 v[68:71], v[156:159], v[188:191], v[68:71]
	v_mfma_f32_16x16x32_bf16 v[64:67], v[164:167], v[188:191], v[64:67]
	v_mfma_f32_16x16x32_bf16 v[60:63], v[156:159], v[196:199], v[60:63]
	v_mfma_f32_16x16x32_bf16 v[56:59], v[164:167], v[196:199], v[56:59]
	v_mfma_f32_16x16x32_bf16 v[44:47], v[156:159], v[204:207], v[44:47]
	v_mfma_f32_16x16x32_bf16 v[40:43], v[164:167], v[204:207], v[40:43]
	v_mfma_f32_16x16x32_bf16 v[24:27], v[156:159], v[212:215], v[24:27]
	v_mfma_f32_16x16x32_bf16 v[20:23], v[164:167], v[212:215], v[20:23]
	s_setprio 0
	s_setprio 1
	v_mfma_f32_16x16x32_bf16 v[52:55], v[168:171], v[184:187], v[52:55]
	v_mfma_f32_16x16x32_bf16 v[48:51], v[176:179], v[184:187], v[48:51]
	v_mfma_f32_16x16x32_bf16 v[32:35], v[168:171], v[192:195], v[32:35]
	v_mfma_f32_16x16x32_bf16 v[28:31], v[176:179], v[192:195], v[28:31]
	v_mfma_f32_16x16x32_bf16 v[16:19], v[168:171], v[200:203], v[16:19]
	v_mfma_f32_16x16x32_bf16 v[12:15], v[176:179], v[200:203], v[12:15]
	v_mfma_f32_16x16x32_bf16 v[8:11], v[168:171], v[208:211], v[8:11]
	v_mfma_f32_16x16x32_bf16 v[4:7], v[176:179], v[208:211], v[4:7]
	v_mfma_f32_16x16x32_bf16 v[52:55], v[172:175], v[188:191], v[52:55]
	v_mfma_f32_16x16x32_bf16 v[48:51], v[180:183], v[188:191], v[48:51]
	v_mfma_f32_16x16x32_bf16 v[32:35], v[172:175], v[196:199], v[32:35]
	v_mfma_f32_16x16x32_bf16 v[28:31], v[180:183], v[196:199], v[28:31]
	v_mfma_f32_16x16x32_bf16 v[16:19], v[172:175], v[204:207], v[16:19]
	v_mfma_f32_16x16x32_bf16 v[12:15], v[180:183], v[204:207], v[12:15]
	v_mfma_f32_16x16x32_bf16 v[8:11], v[172:175], v[212:215], v[8:11]
	v_mfma_f32_16x16x32_bf16 v[4:7], v[180:183], v[212:215], v[4:7]
	s_setprio 0
	s_barrier
	s_add_i32 s13, s13, 2
	s_add_u32 s10, s10, 0x10000
	s_addc_u32 s11, s11, 0
	s_add_u32 vcc_lo, vcc_lo, 0x10000
	s_addc_u32 vcc_hi, vcc_hi, 0
	s_cmpk_gt_u32 s13, 0x55
	s_cbranch_scc0 .LBB0_439
	s_and_b64 vcc, exec, s[6:7]
	s_cbranch_vccz .LBB0_442
	s_barrier

; #define PG8_STAGE(bufoff, gbase, voff) do { _Pragma("unroll") for (int _i = 0; _i < 2; ++_i) \
;         __builtin_amdgcn_global_load_lds((const unsigned*)((const char*)(gbase) + (voff)[_i]), (PG8_LAS unsigned*)(lds + (bufoff) + ldsw + _i * 8192), 16, 0, 0); } while (0)
; #define PG8_LDA(dst, b, h) do { _Pragma("unroll") for (int m = 0; m < 4; ++m) _Pragma("unroll") for (int k = 0; k < 2; ++k) dst[m][k] = *(const PG8_LAS bf16x8*)(lds + PG8_SA(b, h) + aoff + m * 2048 + k * 1024); } while (0)
; #define PG8_LDB(dst, b, h) do { _Pragma("unroll") for (int n = 0; n < 2; ++n) _Pragma("unroll") for (int k = 0; k < 2; ++k) dst[n][k] = *(const PG8_LAS bf16x8*)(lds + PG8_SB(b, h) + boff + n * 2048 + k * 1024); } while (0)
; #define PG8_MMA(ai, bj, At, Bt) do { __builtin_amdgcn_s_setprio(1); _Pragma("unroll") for (int m = 0; m < 4; ++m) _Pragma("unroll") for (int n = 0; n < 2; ++n) _Pragma("unroll") for (int k = 0; k < 2; ++k) \
;         acc[ai][bj][m][n] = __builtin_amdgcn_mfma_f32_16x16x32_bf16(Bt[n][k], At[m][k], acc[ai][bj][m][n], 0, 0, 0); __builtin_amdgcn_s_setprio(0); } while (0)
; #define PG8_WAIT_V(n) asm volatile("s_waitcnt vmcnt(" #n ")" ::: "memory")
; #define PG8_WAIT_L(n) asm volatile("s_waitcnt lgkmcnt(" #n ")" ::: "memory")
; #define PG8_BAR __builtin_amdgcn_s_barrier()
; #define PG8_SCHED __builtin_amdgcn_sched_barrier(0)
; template <class Epi, class Sched, bool ALIGN_EPI = false, bool SP2 = false, bool ABLK = false, bool BBLK = false>
; __device__ __forceinline__ void gemm_phase(PG8_LAS unsigned char* lds, const Gemm g, const Sched& S, const Epi& E) {
;     ...
;             PG8_LDB(B0, 0, 0); PG8_LDB(B1, 0, 1); PG8_SCHED; PG8_LDA(At, 0, 0); PG8_STAGE(PG8_SA(1, 1), a1 + hstepA, voffA);
;             PG8_WAIT_V(8); PG8_WAIT_L(0); PG8_BAR; PG8_MMA(0, 0, At, B0); PG8_MMA(0, 1, At, B1); PG8_BAR; PG8_SCHED;
;             PG8_LDA(At, 0, 1); PG8_STAGE(PG8_SB(0, 0), b2, voffB); PG8_STAGE(PG8_SB(0, 1), b2 + hstepB, voffB); PG8_STAGE(PG8_SA(0, 0), a2, voffA);
;             PG8_WAIT_V(8); PG8_WAIT_L(0); PG8_BAR; PG8_MMA(1, 0, At, B0); PG8_MMA(1, 1, At, B1); PG8_BAR; PG8_SCHED;
.LBB0_916:
	s_add_u32 s22, s20, 0x4000
	s_addc_u32 s23, s21, 0
	s_cmp_eq_u32 s13, 28
	s_cselect_b32 s26, s19, s22
	s_cselect_b32 s27, s1, s23
	s_cselect_b32 s24, s65, s70
	s_cselect_b32 s25, s9, s71
	s_add_u32 s22, s26, 0x8000
	s_addc_u32 s23, s27, 0
	s_add_i32 s68, 0, 0x10000
	v_add_u32_e32 v36, s68, v155
	s_add_i32 s77, 0, 0x14000
	ds_read_b128 v[150:153], v36
	ds_read_b128 v[158:161], v36 offset:1024
	ds_read_b128 v[162:165], v36 offset:2048
	ds_read_b128 v[166:169], v36 offset:3072
	v_add_u32_e32 v36, s77, v155
	ds_read_b128 v[170:173], v36
	ds_read_b128 v[174:177], v36 offset:1024
	ds_read_b128 v[178:181], v36 offset:2048
	ds_read_b128 v[182:185], v36 offset:3072
	s_add_i32 m0, s31, 0xc000
	ds_read_b128 v[186:189], v157
	ds_read_b128 v[190:193], v157 offset:1024
	ds_read_b128 v[194:197], v157 offset:2048
	ds_read_b128 v[198:201], v157 offset:3072
	ds_read_b128 v[202:205], v157 offset:4096
	ds_read_b128 v[206:209], v157 offset:5120
	ds_read_b128 v[210:213], v157 offset:6144
	ds_read_b128 v[214:217], v157 offset:7168
	global_load_lds_dwordx4 v146, s[20:21]
	s_add_i32 m0, s31, 0xe000
	s_nop 0
	global_load_lds_dwordx4 v148, s[20:21]
	s_waitcnt vmcnt(8)
	s_waitcnt lgkmcnt(0)
	v_mfma_f32_16x16x32_bf16 v[132:135], v[150:153], v[186:189], v[132:135]
	v_mfma_f32_16x16x32_bf16 v[128:131], v[162:165], v[186:189], v[128:131]
	v_mfma_f32_16x16x32_bf16 v[124:127], v[150:153], v[194:197], v[124:127]
	v_mfma_f32_16x16x32_bf16 v[116:119], v[162:165], v[194:197], v[116:119]
	s_barrier
	s_setprio 1
	v_mfma_f32_16x16x32_bf16 v[108:111], v[150:153], v[202:205], v[108:111]
	v_mfma_f32_16x16x32_bf16 v[100:103], v[162:165], v[202:205], v[100:103]
	v_mfma_f32_16x16x32_bf16 v[92:95], v[150:153], v[210:213], v[92:95]
	v_mfma_f32_16x16x32_bf16 v[84:87], v[162:165], v[210:213], v[84:87]
	v_mfma_f32_16x16x32_bf16 v[132:135], v[158:161], v[190:193], v[132:135]
	v_mfma_f32_16x16x32_bf16 v[128:131], v[166:169], v[190:193], v[128:131]
	v_mfma_f32_16x16x32_bf16 v[124:127], v[158:161], v[198:201], v[124:127]
	v_mfma_f32_16x16x32_bf16 v[116:119], v[166:169], v[198:201], v[116:119]
	v_mfma_f32_16x16x32_bf16 v[108:111], v[158:161], v[206:209], v[108:111]
	v_mfma_f32_16x16x32_bf16 v[100:103], v[166:169], v[206:209], v[100:103]
	v_mfma_f32_16x16x32_bf16 v[92:95], v[158:161], v[214:217], v[92:95]
	v_mfma_f32_16x16x32_bf16 v[84:87], v[166:169], v[214:217], v[84:87]
	s_setprio 0
	s_setprio 1
	v_mfma_f32_16x16x32_bf16 v[120:123], v[170:173], v[186:189], v[120:123]
	v_mfma_f32_16x16x32_bf16 v[112:115], v[178:181], v[186:189], v[112:115]
	v_mfma_f32_16x16x32_bf16 v[104:107], v[170:173], v[194:197], v[104:107]
	v_mfma_f32_16x16x32_bf16 v[96:99], v[178:181], v[194:197], v[96:99]
	v_mfma_f32_16x16x32_bf16 v[88:91], v[170:173], v[202:205], v[88:91]
	v_mfma_f32_16x16x32_bf16 v[80:83], v[178:181], v[202:205], v[80:83]
	v_mfma_f32_16x16x32_bf16 v[76:79], v[170:173], v[210:213], v[76:79]
	v_mfma_f32_16x16x32_bf16 v[72:75], v[178:181], v[210:213], v[72:75]
	v_mfma_f32_16x16x32_bf16 v[120:123], v[174:177], v[190:193], v[120:123]
	v_mfma_f32_16x16x32_bf16 v[112:115], v[182:185], v[190:193], v[112:115]
	v_mfma_f32_16x16x32_bf16 v[104:107], v[174:177], v[198:201], v[104:107]
	v_mfma_f32_16x16x32_bf16 v[96:99], v[182:185], v[198:201], v[96:99]
	v_mfma_f32_16x16x32_bf16 v[88:91], v[174:177], v[206:209], v[88:91]
	v_mfma_f32_16x16x32_bf16 v[80:83], v[182:185], v[206:209], v[80:83]
	v_mfma_f32_16x16x32_bf16 v[76:79], v[174:177], v[214:217], v[76:79]
	v_mfma_f32_16x16x32_bf16 v[72:75], v[182:185], v[214:217], v[72:75]
	s_setprio 0
	s_barrier
	s_add_i32 s68, s68, s29
	s_mov_b32 m0, s68
	ds_read_b128 v[186:189], v157 offset:16384
	ds_read_b128 v[190:193], v157 offset:17408
	ds_read_b128 v[194:197], v157 offset:18432
	ds_read_b128 v[198:201], v157 offset:19456
	ds_read_b128 v[202:205], v157 offset:20480
	ds_read_b128 v[206:209], v157 offset:21504
	ds_read_b128 v[210:213], v157 offset:22528
	ds_read_b128 v[214:217], v157 offset:23552
	global_load_lds_dwordx4 v140, s[24:25]
	s_add_i32 m0, s68, 0x2000
	s_add_u32 s68, s24, 0x4000
	s_addc_u32 s69, s25, 0
	s_add_i32 s77, s77, s29
	global_load_lds_dwordx4 v136, s[24:25]
	s_mov_b32 m0, s77
	s_nop 0
	global_load_lds_dwordx4 v140, s[68:69]
	s_add_i32 m0, s77, 0x2000
	s_nop 0
	global_load_lds_dwordx4 v136, s[68:69]
	s_mov_b32 m0, s31
	s_nop 0
	global_load_lds_dwordx4 v142, s[26:27]
	s_mov_b32 m0, s34
	s_nop 0
	global_load_lds_dwordx4 v138, s[26:27]
	s_waitcnt vmcnt(8)
	s_waitcnt lgkmcnt(0)
	v_mfma_f32_16x16x32_bf16 v[68:71], v[150:153], v[186:189], v[68:71]
	v_mfma_f32_16x16x32_bf16 v[64:67], v[162:165], v[186:189], v[64:67]
	v_mfma_f32_16x16x32_bf16 v[60:63], v[150:153], v[194:197], v[60:63]
	v_mfma_f32_16x16x32_bf16 v[52:55], v[162:165], v[194:197], v[52:55]
	s_barrier
; #define PG8_STAGE(bufoff, gbase, voff) do { _Pragma("unroll") for (int _i = 0; _i < 2; ++_i) \
;         __builtin_amdgcn_global_load_lds((const unsigned*)((const char*)(gbase) + (voff)[_i]), (PG8_LAS unsigned*)(lds + (bufoff) + ldsw + _i * 8192), 16, 0, 0); } while (0)
; #define PG8_LDA(dst, b, h) do { _Pragma("unroll") for (int m = 0; m < 4; ++m) _Pragma("unroll") for (int k = 0; k < 2; ++k) dst[m][k] = *(const PG8_LAS bf16x8*)(lds + PG8_SA(b, h) + aoff + m * 2048 + k * 1024); } while (0)
; #define PG8_LDB(dst, b, h) do { _Pragma("unroll") for (int n = 0; n < 2; ++n) _Pragma("unroll") for (int k = 0; k < 2; ++k) dst[n][k] = *(const PG8_LAS bf16x8*)(lds + PG8_SB(b, h) + boff + n * 2048 + k * 1024); } while (0)
; #define PG8_MMA(ai, bj, At, Bt) do { __builtin_amdgcn_s_setprio(1); _Pragma("unroll") for (int m = 0; m < 4; ++m) _Pragma("unroll") for (int n = 0; n < 2; ++n) _Pragma("unroll") for (int k = 0; k < 2; ++k) \
;         acc[ai][bj][m][n] = __builtin_amdgcn_mfma_f32_16x16x32_bf16(Bt[n][k], At[m][k], acc[ai][bj][m][n], 0, 0, 0); __builtin_amdgcn_s_setprio(0); } while (0)
; #define PG8_WAIT_V(n) asm volatile("s_waitcnt vmcnt(" #n ")" ::: "memory")
; #define PG8_WAIT_L(n) asm volatile("s_waitcnt lgkmcnt(" #n ")" ::: "memory")
; #define PG8_BAR __builtin_amdgcn_s_barrier()
; #define PG8_SCHED __builtin_amdgcn_sched_barrier(0)
; template <class Epi, class Sched, bool ALIGN_EPI = false, bool SP2 = false, bool ABLK = false, bool BBLK = false>
; __device__ __forceinline__ void gemm_phase(PG8_LAS unsigned char* lds, const Gemm g, const Sched& S, const Epi& E) {
;     ...
;             PG8_WAIT_V(8); PG8_WAIT_L(0); PG8_BAR; PG8_MMA(1, 0, At, B0); PG8_MMA(1, 1, At, B1); PG8_BAR; PG8_SCHED;
;             PG8_LDB(B0, 1, 0); PG8_LDB(B1, 1, 1); PG8_SCHED; PG8_LDA(At, 1, 0); PG8_STAGE(PG8_SA(0, 1), a2 + hstepA, voffA);
;             PG8_WAIT_V(8); PG8_WAIT_L(0); PG8_BAR; PG8_MMA(0, 0, At, B0); PG8_MMA(0, 1, At, B1); PG8_BAR; PG8_SCHED;
	s_setprio 1
	v_mfma_f32_16x16x32_bf16 v[44:47], v[150:153], v[202:205], v[44:47]
	v_mfma_f32_16x16x32_bf16 v[32:35], v[162:165], v[202:205], v[32:35]
	v_mfma_f32_16x16x32_bf16 v[24:27], v[150:153], v[210:213], v[24:27]
	v_mfma_f32_16x16x32_bf16 v[16:19], v[162:165], v[210:213], v[16:19]
	v_mfma_f32_16x16x32_bf16 v[68:71], v[158:161], v[190:193], v[68:71]
	v_mfma_f32_16x16x32_bf16 v[64:67], v[166:169], v[190:193], v[64:67]
	v_mfma_f32_16x16x32_bf16 v[60:63], v[158:161], v[198:201], v[60:63]
	v_mfma_f32_16x16x32_bf16 v[52:55], v[166:169], v[198:201], v[52:55]
	v_mfma_f32_16x16x32_bf16 v[44:47], v[158:161], v[206:209], v[44:47]
	v_mfma_f32_16x16x32_bf16 v[32:35], v[166:169], v[206:209], v[32:35]
	v_mfma_f32_16x16x32_bf16 v[24:27], v[158:161], v[214:217], v[24:27]
	v_mfma_f32_16x16x32_bf16 v[16:19], v[166:169], v[214:217], v[16:19]
	s_setprio 0
	s_setprio 1
	v_mfma_f32_16x16x32_bf16 v[56:59], v[170:173], v[186:189], v[56:59]
	v_mfma_f32_16x16x32_bf16 v[48:51], v[178:181], v[186:189], v[48:51]
	v_mfma_f32_16x16x32_bf16 v[40:43], v[170:173], v[194:197], v[40:43]
	v_mfma_f32_16x16x32_bf16 v[28:31], v[178:181], v[194:197], v[28:31]
	v_mfma_f32_16x16x32_bf16 v[20:23], v[170:173], v[202:205], v[20:23]
	v_mfma_f32_16x16x32_bf16 v[12:15], v[178:181], v[202:205], v[12:15]
	v_mfma_f32_16x16x32_bf16 v[8:11], v[170:173], v[210:213], v[8:11]
	v_mfma_f32_16x16x32_bf16 v[4:7], v[178:181], v[210:213], v[4:7]
	v_mfma_f32_16x16x32_bf16 v[56:59], v[174:177], v[190:193], v[56:59]
	v_mfma_f32_16x16x32_bf16 v[48:51], v[182:185], v[190:193], v[48:51]
	v_mfma_f32_16x16x32_bf16 v[40:43], v[174:177], v[198:201], v[40:43]
	v_mfma_f32_16x16x32_bf16 v[28:31], v[182:185], v[198:201], v[28:31]
	v_mfma_f32_16x16x32_bf16 v[20:23], v[174:177], v[206:209], v[20:23]
	v_mfma_f32_16x16x32_bf16 v[12:15], v[182:185], v[206:209], v[12:15]
	v_mfma_f32_16x16x32_bf16 v[8:11], v[174:177], v[214:217], v[8:11]
	v_mfma_f32_16x16x32_bf16 v[4:7], v[182:185], v[214:217], v[4:7]
	s_setprio 0
	s_barrier
	s_add_i32 s68, 0, 0x18000
	v_add_u32_e32 v36, s68, v155
	s_add_i32 s69, 0, 0x1c000
	ds_read_b128 v[150:153], v36
	ds_read_b128 v[158:161], v36 offset:1024
	ds_read_b128 v[162:165], v36 offset:2048
	ds_read_b128 v[166:169], v36 offset:3072
	v_add_u32_e32 v36, s69, v155
	ds_read_b128 v[170:173], v36
	ds_read_b128 v[174:177], v36 offset:1024
	ds_read_b128 v[178:181], v36 offset:2048
	ds_read_b128 v[182:185], v36 offset:3072
	s_add_u32 s26, s26, 0x4000
	s_addc_u32 s27, s27, 0
	s_mov_b32 m0, s35
	ds_read_b128 v[186:189], v157 offset:32768
	ds_read_b128 v[190:193], v157 offset:33792
	ds_read_b128 v[194:197], v157 offset:34816
	ds_read_b128 v[198:201], v157 offset:35840
	ds_read_b128 v[202:205], v157 offset:36864
	ds_read_b128 v[206:209], v157 offset:37888
	ds_read_b128 v[210:213], v157 offset:38912
	ds_read_b128 v[214:217], v157 offset:39936
	global_load_lds_dwordx4 v142, s[26:27]
	s_mov_b32 m0, s36
	s_nop 0
	global_load_lds_dwordx4 v138, s[26:27]
	s_waitcnt vmcnt(8)
	s_waitcnt lgkmcnt(0)
	v_mfma_f32_16x16x32_bf16 v[132:135], v[150:153], v[186:189], v[132:135]
	v_mfma_f32_16x16x32_bf16 v[128:131], v[162:165], v[186:189], v[128:131]
	v_mfma_f32_16x16x32_bf16 v[124:127], v[150:153], v[194:197], v[124:127]
	v_mfma_f32_16x16x32_bf16 v[116:119], v[162:165], v[194:197], v[116:119]
	s_barrier
	s_setprio 1
	v_mfma_f32_16x16x32_bf16 v[108:111], v[150:153], v[202:205], v[108:111]
	v_mfma_f32_16x16x32_bf16 v[100:103], v[162:165], v[202:205], v[100:103]
	v_mfma_f32_16x16x32_bf16 v[92:95], v[150:153], v[210:213], v[92:95]
	v_mfma_f32_16x16x32_bf16 v[84:87], v[162:165], v[210:213], v[84:87]
	v_mfma_f32_16x16x32_bf16 v[132:135], v[158:161], v[190:193], v[132:135]
	v_mfma_f32_16x16x32_bf16 v[128:131], v[166:169], v[190:193], v[128:131]
	v_mfma_f32_16x16x32_bf16 v[124:127], v[158:161], v[198:201], v[124:127]
	v_mfma_f32_16x16x32_bf16 v[116:119], v[166:169], v[198:201], v[116:119]
	v_mfma_f32_16x16x32_bf16 v[108:111], v[158:161], v[206:209], v[108:111]
	v_mfma_f32_16x16x32_bf16 v[100:103], v[166:169], v[206:209], v[100:103]
	v_mfma_f32_16x16x32_bf16 v[92:95], v[158:161], v[214:217], v[92:95]
	v_mfma_f32_16x16x32_bf16 v[84:87], v[166:169], v[214:217], v[84:87]
	s_setprio 0
	s_setprio 1
	v_mfma_f32_16x16x32_bf16 v[120:123], v[170:173], v[186:189], v[120:123]
	v_mfma_f32_16x16x32_bf16 v[112:115], v[178:181], v[186:189], v[112:115]
	v_mfma_f32_16x16x32_bf16 v[104:107], v[170:173], v[194:197], v[104:107]
	v_mfma_f32_16x16x32_bf16 v[96:99], v[178:181], v[194:197], v[96:99]
	v_mfma_f32_16x16x32_bf16 v[88:91], v[170:173], v[202:205], v[88:91]
	v_mfma_f32_16x16x32_bf16 v[80:83], v[178:181], v[202:205], v[80:83]
	v_mfma_f32_16x16x32_bf16 v[76:79], v[170:173], v[210:213], v[76:79]
	v_mfma_f32_16x16x32_bf16 v[72:75], v[178:181], v[210:213], v[72:75]
	v_mfma_f32_16x16x32_bf16 v[120:123], v[174:177], v[190:193], v[120:123]
	v_mfma_f32_16x16x32_bf16 v[112:115], v[182:185], v[190:193], v[112:115]
	v_mfma_f32_16x16x32_bf16 v[104:107], v[174:177], v[198:201], v[104:107]
	v_mfma_f32_16x16x32_bf16 v[96:99], v[182:185], v[198:201], v[96:99]
	v_mfma_f32_16x16x32_bf16 v[88:91], v[174:177], v[206:209], v[88:91]
	v_mfma_f32_16x16x32_bf16 v[80:83], v[182:185], v[206:209], v[80:83]
	v_mfma_f32_16x16x32_bf16 v[76:79], v[174:177], v[214:217], v[76:79]
	v_mfma_f32_16x16x32_bf16 v[72:75], v[182:185], v[214:217], v[72:75]
	s_setprio 0
	s_barrier
; #define PG8_STAGE(bufoff, gbase, voff) do { _Pragma("unroll") for (int _i = 0; _i < 2; ++_i) \
;         __builtin_amdgcn_global_load_lds((const unsigned*)((const char*)(gbase) + (voff)[_i]), (PG8_LAS unsigned*)(lds + (bufoff) + ldsw + _i * 8192), 16, 0, 0); } while (0)
; #define PG8_LDA(dst, b, h) do { _Pragma("unroll") for (int m = 0; m < 4; ++m) _Pragma("unroll") for (int k = 0; k < 2; ++k) dst[m][k] = *(const PG8_LAS bf16x8*)(lds + PG8_SA(b, h) + aoff + m * 2048 + k * 1024); } while (0)
; #define PG8_MMA(ai, bj, At, Bt) do { __builtin_amdgcn_s_setprio(1); _Pragma("unroll") for (int m = 0; m < 4; ++m) _Pragma("unroll") for (int n = 0; n < 2; ++n) _Pragma("unroll") for (int k = 0; k < 2; ++k) \
;         acc[ai][bj][m][n] = __builtin_amdgcn_mfma_f32_16x16x32_bf16(Bt[n][k], At[m][k], acc[ai][bj][m][n], 0, 0, 0); __builtin_amdgcn_s_setprio(0); } while (0)
; #define PG8_WAIT_V(n) asm volatile("s_waitcnt vmcnt(" #n ")" ::: "memory")
; #define PG8_WAIT_L(n) asm volatile("s_waitcnt lgkmcnt(" #n ")" ::: "memory")
; #define PG8_BAR __builtin_amdgcn_s_barrier()
; #define PG8_SCHED __builtin_amdgcn_sched_barrier(0)
; template <class Epi, class Sched, bool ALIGN_EPI = false, bool SP2 = false, bool ABLK = false, bool BBLK = false>
; __device__ __forceinline__ void gemm_phase(PG8_LAS unsigned char* lds, const Gemm g, const Sched& S, const Epi& E) {
;     ...
;             PG8_LDA(At, 1, 1); PG8_STAGE(PG8_SB(1, 0), b3, voffB); PG8_STAGE(PG8_SB(1, 1), b3 + hstepB, voffB); PG8_STAGE(PG8_SA(1, 0), a3, voffA);
;             PG8_WAIT_V(8); PG8_WAIT_L(0); PG8_BAR; PG8_MMA(1, 0, At, B0); PG8_MMA(1, 1, At, B1); PG8_BAR; PG8_SCHED;
	s_add_u32 s26, s24, 0x8000
	s_addc_u32 s27, s25, 0
	s_add_i32 s68, s68, s29
	s_mov_b32 m0, s68
	ds_read_b128 v[186:189], v157 offset:49152
	ds_read_b128 v[190:193], v157 offset:50176
	ds_read_b128 v[194:197], v157 offset:51200
	ds_read_b128 v[198:201], v157 offset:52224
	ds_read_b128 v[202:205], v157 offset:53248
	ds_read_b128 v[206:209], v157 offset:54272
	ds_read_b128 v[210:213], v157 offset:55296
	ds_read_b128 v[214:217], v157 offset:56320
	global_load_lds_dwordx4 v140, s[26:27]
	s_add_i32 m0, s68, 0x2000
	s_add_u32 s24, s24, 0xc000
	s_addc_u32 s25, s25, 0
	global_load_lds_dwordx4 v136, s[26:27]
	s_add_i32 s26, s69, s29
	s_mov_b32 m0, s26
	s_nop 0
	global_load_lds_dwordx4 v140, s[24:25]
	s_add_i32 m0, s26, 0x2000
	s_nop 0
	global_load_lds_dwordx4 v136, s[24:25]
	s_mov_b32 m0, s37
	s_nop 0
	global_load_lds_dwordx4 v142, s[22:23]
	s_mov_b32 m0, s62
	s_nop 0
	global_load_lds_dwordx4 v138, s[22:23]
	s_waitcnt vmcnt(8)
	s_waitcnt lgkmcnt(0)
	v_mfma_f32_16x16x32_bf16 v[68:71], v[150:153], v[186:189], v[68:71]
	v_mfma_f32_16x16x32_bf16 v[64:67], v[162:165], v[186:189], v[64:67]
	v_mfma_f32_16x16x32_bf16 v[60:63], v[150:153], v[194:197], v[60:63]
	v_mfma_f32_16x16x32_bf16 v[52:55], v[162:165], v[194:197], v[52:55]
	s_barrier
	s_setprio 1
	v_mfma_f32_16x16x32_bf16 v[44:47], v[150:153], v[202:205], v[44:47]
	v_mfma_f32_16x16x32_bf16 v[32:35], v[162:165], v[202:205], v[32:35]
	v_mfma_f32_16x16x32_bf16 v[24:27], v[150:153], v[210:213], v[24:27]
	v_mfma_f32_16x16x32_bf16 v[16:19], v[162:165], v[210:213], v[16:19]
	v_mfma_f32_16x16x32_bf16 v[68:71], v[158:161], v[190:193], v[68:71]
	v_mfma_f32_16x16x32_bf16 v[64:67], v[166:169], v[190:193], v[64:67]
	v_mfma_f32_16x16x32_bf16 v[60:63], v[158:161], v[198:201], v[60:63]
	v_mfma_f32_16x16x32_bf16 v[52:55], v[166:169], v[198:201], v[52:55]
	v_mfma_f32_16x16x32_bf16 v[44:47], v[158:161], v[206:209], v[44:47]
	v_mfma_f32_16x16x32_bf16 v[32:35], v[166:169], v[206:209], v[32:35]
	v_mfma_f32_16x16x32_bf16 v[24:27], v[158:161], v[214:217], v[24:27]
	v_mfma_f32_16x16x32_bf16 v[16:19], v[166:169], v[214:217], v[16:19]
	s_setprio 0
	s_setprio 1
	v_mfma_f32_16x16x32_bf16 v[56:59], v[170:173], v[186:189], v[56:59]
	v_mfma_f32_16x16x32_bf16 v[48:51], v[178:181], v[186:189], v[48:51]
	v_mfma_f32_16x16x32_bf16 v[40:43], v[170:173], v[194:197], v[40:43]
	v_mfma_f32_16x16x32_bf16 v[28:31], v[178:181], v[194:197], v[28:31]
	v_mfma_f32_16x16x32_bf16 v[20:23], v[170:173], v[202:205], v[20:23]
	v_mfma_f32_16x16x32_bf16 v[12:15], v[178:181], v[202:205], v[12:15]
	v_mfma_f32_16x16x32_bf16 v[8:11], v[170:173], v[210:213], v[8:11]
	v_mfma_f32_16x16x32_bf16 v[4:7], v[178:181], v[210:213], v[4:7]
	v_mfma_f32_16x16x32_bf16 v[56:59], v[174:177], v[190:193], v[56:59]
	v_mfma_f32_16x16x32_bf16 v[48:51], v[182:185], v[190:193], v[48:51]
	v_mfma_f32_16x16x32_bf16 v[40:43], v[174:177], v[198:201], v[40:43]
	v_mfma_f32_16x16x32_bf16 v[28:31], v[182:185], v[198:201], v[28:31]
	v_mfma_f32_16x16x32_bf16 v[20:23], v[174:177], v[206:209], v[20:23]
	v_mfma_f32_16x16x32_bf16 v[12:15], v[182:185], v[206:209], v[12:15]
	v_mfma_f32_16x16x32_bf16 v[8:11], v[174:177], v[214:217], v[8:11]
	v_mfma_f32_16x16x32_bf16 v[4:7], v[182:185], v[214:217], v[4:7]
	s_setprio 0
	s_barrier
	s_add_i32 s13, s13, 2
	s_add_u32 s20, s20, 0x10000
	s_addc_u32 s21, s21, 0
	s_add_u32 s70, s70, 0x10000
	s_addc_u32 s71, s71, 0
	s_cmp_gt_u32 s13, 29
	s_cbranch_scc0 .LBB0_916
	s_and_b64 vcc, exec, s[6:7]
	s_cbranch_vccz .LBB0_919
	s_barrier

; #define PG8_STAGE(bufoff, gbase, voff) do { _Pragma("unroll") for (int _i = 0; _i < 2; ++_i) \
;         __builtin_amdgcn_global_load_lds((const unsigned*)((const char*)(gbase) + (voff)[_i]), (PG8_LAS unsigned*)(lds + (bufoff) + ldsw + _i * 8192), 16, 0, 0); } while (0)
; #define PG8_LDA(dst, b, h) do { _Pragma("unroll") for (int m = 0; m < 4; ++m) _Pragma("unroll") for (int k = 0; k < 2; ++k) dst[m][k] = *(const PG8_LAS bf16x8*)(lds + PG8_SA(b, h) + aoff + m * 2048 + k * 1024); } while (0)
; #define PG8_LDB(dst, b, h) do { _Pragma("unroll") for (int n = 0; n < 2; ++n) _Pragma("unroll") for (int k = 0; k < 2; ++k) dst[n][k] = *(const PG8_LAS bf16x8*)(lds + PG8_SB(b, h) + boff + n * 2048 + k * 1024); } while (0)
; #define PG8_MMA(ai, bj, At, Bt) do { __builtin_amdgcn_s_setprio(1); _Pragma("unroll") for (int m = 0; m < 4; ++m) _Pragma("unroll") for (int n = 0; n < 2; ++n) _Pragma("unroll") for (int k = 0; k < 2; ++k) \
;         acc[ai][bj][m][n] = __builtin_amdgcn_mfma_f32_16x16x32_bf16(Bt[n][k], At[m][k], acc[ai][bj][m][n], 0, 0, 0); __builtin_amdgcn_s_setprio(0); } while (0)
; #define PG8_WAIT_V(n) asm volatile("s_waitcnt vmcnt(" #n ")" ::: "memory")
; #define PG8_WAIT_L(n) asm volatile("s_waitcnt lgkmcnt(" #n ")" ::: "memory")
; #define PG8_BAR __builtin_amdgcn_s_barrier()
; #define PG8_SCHED __builtin_amdgcn_sched_barrier(0)
; template <class Epi, class Sched, bool ALIGN_EPI = false, bool SP2 = false, bool ABLK = false, bool BBLK = false>
; __device__ __forceinline__ void gemm_phase(PG8_LAS unsigned char* lds, const Gemm g, const Sched& S, const Epi& E) {
;     ...
;             PG8_LDB(B0, 0, 0); PG8_LDB(B1, 0, 1); PG8_SCHED; PG8_LDA(At, 0, 0); PG8_STAGE(PG8_SA(1, 1), a1 + hstepA, voffA);
;             PG8_WAIT_V(8); PG8_WAIT_L(0); PG8_BAR; PG8_MMA(0, 0, At, B0); PG8_MMA(0, 1, At, B1); PG8_BAR; PG8_SCHED;
;             PG8_LDA(At, 0, 1); PG8_STAGE(PG8_SB(0, 0), b2, voffB); PG8_STAGE(PG8_SB(0, 1), b2 + hstepB, voffB); PG8_STAGE(PG8_SA(0, 0), a2, voffA);
;             PG8_WAIT_V(8); PG8_WAIT_L(0); PG8_BAR; PG8_MMA(1, 0, At, B0); PG8_MMA(1, 1, At, B1); PG8_BAR; PG8_SCHED;
.LBB0_2111:
	s_add_u32 s24, s22, 0x4000
	s_addc_u32 s25, s23, 0
	s_cmp_eq_u32 s13, 28
	s_cselect_b32 s28, s17, s24
	s_cselect_b32 s29, s12, s25
	s_cselect_b32 s26, s77, s82
	s_cselect_b32 s27, s11, vcc_lo
	s_add_u32 s24, s28, 0x8000
	s_addc_u32 s25, s29, 0
	s_add_i32 s68, 0, 0x10000
	v_add_u32_e32 v151, s68, v148
	s_add_i32 s88, 0, 0x14000
	ds_read_b128 v[36:39], v151
	ds_read_b128 v[152:155], v151 offset:1024
	ds_read_b128 v[156:159], v151 offset:2048
	ds_read_b128 v[160:163], v151 offset:3072
	v_add_u32_e32 v151, s88, v148
	ds_read_b128 v[164:167], v151
	ds_read_b128 v[168:171], v151 offset:1024
	ds_read_b128 v[172:175], v151 offset:2048
	ds_read_b128 v[176:179], v151 offset:3072
	s_add_i32 m0, s9, 0xc000
	ds_read_b128 v[180:183], v150
	ds_read_b128 v[184:187], v150 offset:1024
	ds_read_b128 v[188:191], v150 offset:2048
	ds_read_b128 v[192:195], v150 offset:3072
	ds_read_b128 v[196:199], v150 offset:4096
	ds_read_b128 v[200:203], v150 offset:5120
	ds_read_b128 v[204:207], v150 offset:6144
	ds_read_b128 v[208:211], v150 offset:7168
	global_load_lds_dwordx4 v144, s[22:23]
	s_add_i32 m0, s9, 0xe000
	s_nop 0
	global_load_lds_dwordx4 v146, s[22:23]
	s_waitcnt vmcnt(8)
	s_waitcnt lgkmcnt(0)
	v_mfma_f32_16x16x32_bf16 v[132:135], v[36:39], v[180:183], v[132:135]
	v_mfma_f32_16x16x32_bf16 v[128:131], v[156:159], v[180:183], v[128:131]
	v_mfma_f32_16x16x32_bf16 v[124:127], v[36:39], v[188:191], v[124:127]
	v_mfma_f32_16x16x32_bf16 v[120:123], v[156:159], v[188:191], v[120:123]
	s_barrier
	s_setprio 1
	v_mfma_f32_16x16x32_bf16 v[108:111], v[36:39], v[196:199], v[108:111]
	v_mfma_f32_16x16x32_bf16 v[104:107], v[156:159], v[196:199], v[104:107]
	v_mfma_f32_16x16x32_bf16 v[92:95], v[36:39], v[204:207], v[92:95]
	v_mfma_f32_16x16x32_bf16 v[88:91], v[156:159], v[204:207], v[88:91]
	v_mfma_f32_16x16x32_bf16 v[132:135], v[152:155], v[184:187], v[132:135]
	v_mfma_f32_16x16x32_bf16 v[128:131], v[160:163], v[184:187], v[128:131]
	v_mfma_f32_16x16x32_bf16 v[124:127], v[152:155], v[192:195], v[124:127]
	v_mfma_f32_16x16x32_bf16 v[120:123], v[160:163], v[192:195], v[120:123]
	v_mfma_f32_16x16x32_bf16 v[108:111], v[152:155], v[200:203], v[108:111]
	v_mfma_f32_16x16x32_bf16 v[104:107], v[160:163], v[200:203], v[104:107]
	v_mfma_f32_16x16x32_bf16 v[92:95], v[152:155], v[208:211], v[92:95]
	v_mfma_f32_16x16x32_bf16 v[88:91], v[160:163], v[208:211], v[88:91]
	s_setprio 0
	s_setprio 1
	v_mfma_f32_16x16x32_bf16 v[116:119], v[164:167], v[180:183], v[116:119]
	v_mfma_f32_16x16x32_bf16 v[112:115], v[172:175], v[180:183], v[112:115]
	v_mfma_f32_16x16x32_bf16 v[100:103], v[164:167], v[188:191], v[100:103]
	v_mfma_f32_16x16x32_bf16 v[96:99], v[172:175], v[188:191], v[96:99]
	v_mfma_f32_16x16x32_bf16 v[84:87], v[164:167], v[196:199], v[84:87]
	v_mfma_f32_16x16x32_bf16 v[80:83], v[172:175], v[196:199], v[80:83]
	v_mfma_f32_16x16x32_bf16 v[76:79], v[164:167], v[204:207], v[76:79]
	v_mfma_f32_16x16x32_bf16 v[72:75], v[172:175], v[204:207], v[72:75]
	v_mfma_f32_16x16x32_bf16 v[116:119], v[168:171], v[184:187], v[116:119]
	v_mfma_f32_16x16x32_bf16 v[112:115], v[176:179], v[184:187], v[112:115]
	v_mfma_f32_16x16x32_bf16 v[100:103], v[168:171], v[192:195], v[100:103]
	v_mfma_f32_16x16x32_bf16 v[96:99], v[176:179], v[192:195], v[96:99]
	v_mfma_f32_16x16x32_bf16 v[84:87], v[168:171], v[200:203], v[84:87]
	v_mfma_f32_16x16x32_bf16 v[80:83], v[176:179], v[200:203], v[80:83]
	v_mfma_f32_16x16x32_bf16 v[76:79], v[168:171], v[208:211], v[76:79]
	v_mfma_f32_16x16x32_bf16 v[72:75], v[176:179], v[208:211], v[72:75]
	s_setprio 0
	s_barrier
	s_add_i32 s68, s68, s34
	s_mov_b32 m0, s68
	ds_read_b128 v[180:183], v150 offset:16384
	ds_read_b128 v[184:187], v150 offset:17408
	ds_read_b128 v[188:191], v150 offset:18432
	ds_read_b128 v[192:195], v150 offset:19456
	ds_read_b128 v[196:199], v150 offset:20480
	ds_read_b128 v[200:203], v150 offset:21504
	ds_read_b128 v[204:207], v150 offset:22528
	ds_read_b128 v[208:211], v150 offset:23552
	global_load_lds_dwordx4 v138, s[26:27]
	s_add_i32 m0, s68, 0x2000
	s_add_u32 s68, s26, 0x4000
	s_addc_u32 s69, s27, 0
	s_add_i32 s88, s88, s34
	global_load_lds_dwordx4 v142, s[26:27]
	s_mov_b32 m0, s88
	s_nop 0
	global_load_lds_dwordx4 v138, s[68:69]
	s_add_i32 m0, s88, 0x2000
	s_nop 0
	global_load_lds_dwordx4 v142, s[68:69]
	s_mov_b32 m0, s9
	s_nop 0
	global_load_lds_dwordx4 v136, s[28:29]
	s_mov_b32 m0, s35
	s_nop 0
	global_load_lds_dwordx4 v140, s[28:29]
	s_waitcnt vmcnt(8)
	s_waitcnt lgkmcnt(0)
	v_mfma_f32_16x16x32_bf16 v[68:71], v[36:39], v[180:183], v[68:71]
	v_mfma_f32_16x16x32_bf16 v[64:67], v[156:159], v[180:183], v[64:67]
	v_mfma_f32_16x16x32_bf16 v[60:63], v[36:39], v[188:191], v[60:63]
	v_mfma_f32_16x16x32_bf16 v[56:59], v[156:159], v[188:191], v[56:59]
	s_barrier
; #define PG8_STAGE(bufoff, gbase, voff) do { _Pragma("unroll") for (int _i = 0; _i < 2; ++_i) \
;         __builtin_amdgcn_global_load_lds((const unsigned*)((const char*)(gbase) + (voff)[_i]), (PG8_LAS unsigned*)(lds + (bufoff) + ldsw + _i * 8192), 16, 0, 0); } while (0)
; #define PG8_LDA(dst, b, h) do { _Pragma("unroll") for (int m = 0; m < 4; ++m) _Pragma("unroll") for (int k = 0; k < 2; ++k) dst[m][k] = *(const PG8_LAS bf16x8*)(lds + PG8_SA(b, h) + aoff + m * 2048 + k * 1024); } while (0)
; #define PG8_LDB(dst, b, h) do { _Pragma("unroll") for (int n = 0; n < 2; ++n) _Pragma("unroll") for (int k = 0; k < 2; ++k) dst[n][k] = *(const PG8_LAS bf16x8*)(lds + PG8_SB(b, h) + boff + n * 2048 + k * 1024); } while (0)
; #define PG8_MMA(ai, bj, At, Bt) do { __builtin_amdgcn_s_setprio(1); _Pragma("unroll") for (int m = 0; m < 4; ++m) _Pragma("unroll") for (int n = 0; n < 2; ++n) _Pragma("unroll") for (int k = 0; k < 2; ++k) \
;         acc[ai][bj][m][n] = __builtin_amdgcn_mfma_f32_16x16x32_bf16(Bt[n][k], At[m][k], acc[ai][bj][m][n], 0, 0, 0); __builtin_amdgcn_s_setprio(0); } while (0)
; #define PG8_WAIT_V(n) asm volatile("s_waitcnt vmcnt(" #n ")" ::: "memory")
; #define PG8_WAIT_L(n) asm volatile("s_waitcnt lgkmcnt(" #n ")" ::: "memory")
; #define PG8_BAR __builtin_amdgcn_s_barrier()
; #define PG8_SCHED __builtin_amdgcn_sched_barrier(0)
; template <class Epi, class Sched, bool ALIGN_EPI = false, bool SP2 = false, bool ABLK = false, bool BBLK = false>
; __device__ __forceinline__ void gemm_phase(PG8_LAS unsigned char* lds, const Gemm g, const Sched& S, const Epi& E) {
;     ...
;             PG8_WAIT_V(8); PG8_WAIT_L(0); PG8_BAR; PG8_MMA(1, 0, At, B0); PG8_MMA(1, 1, At, B1); PG8_BAR; PG8_SCHED;
;             PG8_LDB(B0, 1, 0); PG8_LDB(B1, 1, 1); PG8_SCHED; PG8_LDA(At, 1, 0); PG8_STAGE(PG8_SA(0, 1), a2 + hstepA, voffA);
;             PG8_WAIT_V(8); PG8_WAIT_L(0); PG8_BAR; PG8_MMA(0, 0, At, B0); PG8_MMA(0, 1, At, B1); PG8_BAR; PG8_SCHED;
	s_setprio 1
	v_mfma_f32_16x16x32_bf16 v[44:47], v[36:39], v[196:199], v[44:47]
	v_mfma_f32_16x16x32_bf16 v[40:43], v[156:159], v[196:199], v[40:43]
	v_mfma_f32_16x16x32_bf16 v[24:27], v[36:39], v[204:207], v[24:27]
	v_mfma_f32_16x16x32_bf16 v[20:23], v[156:159], v[204:207], v[20:23]
	v_mfma_f32_16x16x32_bf16 v[68:71], v[152:155], v[184:187], v[68:71]
	v_mfma_f32_16x16x32_bf16 v[64:67], v[160:163], v[184:187], v[64:67]
	v_mfma_f32_16x16x32_bf16 v[60:63], v[152:155], v[192:195], v[60:63]
	v_mfma_f32_16x16x32_bf16 v[56:59], v[160:163], v[192:195], v[56:59]
	v_mfma_f32_16x16x32_bf16 v[44:47], v[152:155], v[200:203], v[44:47]
	v_mfma_f32_16x16x32_bf16 v[40:43], v[160:163], v[200:203], v[40:43]
	v_mfma_f32_16x16x32_bf16 v[24:27], v[152:155], v[208:211], v[24:27]
	v_mfma_f32_16x16x32_bf16 v[20:23], v[160:163], v[208:211], v[20:23]
	s_setprio 0
	s_setprio 1
	v_mfma_f32_16x16x32_bf16 v[48:51], v[172:175], v[180:183], v[48:51]
	v_mfma_f32_16x16x32_bf16 v[32:35], v[164:167], v[188:191], v[32:35]
	v_mfma_f32_16x16x32_bf16 v[28:31], v[172:175], v[188:191], v[28:31]
	v_mfma_f32_16x16x32_bf16 v[16:19], v[164:167], v[196:199], v[16:19]
	v_mfma_f32_16x16x32_bf16 v[12:15], v[172:175], v[196:199], v[12:15]
	v_mfma_f32_16x16x32_bf16 v[8:11], v[164:167], v[204:207], v[8:11]
	v_mfma_f32_16x16x32_bf16 v[4:7], v[172:175], v[204:207], v[4:7]
	v_mfma_f32_16x16x32_bf16 v[36:39], v[164:167], v[180:183], v[52:55]
	v_mfma_f32_16x16x32_bf16 v[48:51], v[176:179], v[184:187], v[48:51]
	v_mfma_f32_16x16x32_bf16 v[32:35], v[168:171], v[192:195], v[32:35]
	v_mfma_f32_16x16x32_bf16 v[28:31], v[176:179], v[192:195], v[28:31]
	v_mfma_f32_16x16x32_bf16 v[16:19], v[168:171], v[200:203], v[16:19]
	v_mfma_f32_16x16x32_bf16 v[12:15], v[176:179], v[200:203], v[12:15]
	v_mfma_f32_16x16x32_bf16 v[8:11], v[168:171], v[208:211], v[8:11]
	v_mfma_f32_16x16x32_bf16 v[4:7], v[176:179], v[208:211], v[4:7]
	v_mfma_f32_16x16x32_bf16 v[36:39], v[168:171], v[184:187], v[36:39]
	s_setprio 0
	s_barrier
	s_add_i32 s68, 0, 0x18000
	v_add_u32_e32 v151, s68, v148
	s_add_i32 s69, 0, 0x1c000
	ds_read_b128 v[52:55], v151
	ds_read_b128 v[152:155], v151 offset:1024
	ds_read_b128 v[156:159], v151 offset:2048
	ds_read_b128 v[160:163], v151 offset:3072
	v_add_u32_e32 v151, s69, v148
	ds_read_b128 v[164:167], v151
	ds_read_b128 v[168:171], v151 offset:1024
	ds_read_b128 v[172:175], v151 offset:2048
	ds_read_b128 v[176:179], v151 offset:3072
	s_add_u32 s28, s28, 0x4000
	s_addc_u32 s29, s29, 0
	s_mov_b32 m0, s36
	ds_read_b128 v[180:183], v150 offset:32768
	ds_read_b128 v[184:187], v150 offset:33792
	ds_read_b128 v[188:191], v150 offset:34816
	ds_read_b128 v[192:195], v150 offset:35840
	ds_read_b128 v[196:199], v150 offset:36864
	ds_read_b128 v[200:203], v150 offset:37888
	ds_read_b128 v[204:207], v150 offset:38912
	ds_read_b128 v[208:211], v150 offset:39936
	global_load_lds_dwordx4 v136, s[28:29]
	s_mov_b32 m0, s37
	s_nop 0
	global_load_lds_dwordx4 v140, s[28:29]
	s_waitcnt vmcnt(8)
	s_waitcnt lgkmcnt(0)
	v_mfma_f32_16x16x32_bf16 v[132:135], v[52:55], v[180:183], v[132:135]
	v_mfma_f32_16x16x32_bf16 v[128:131], v[156:159], v[180:183], v[128:131]
	v_mfma_f32_16x16x32_bf16 v[124:127], v[52:55], v[188:191], v[124:127]
	v_mfma_f32_16x16x32_bf16 v[120:123], v[156:159], v[188:191], v[120:123]
	s_barrier
	s_setprio 1
	v_mfma_f32_16x16x32_bf16 v[108:111], v[52:55], v[196:199], v[108:111]
	v_mfma_f32_16x16x32_bf16 v[104:107], v[156:159], v[196:199], v[104:107]
	v_mfma_f32_16x16x32_bf16 v[92:95], v[52:55], v[204:207], v[92:95]
	v_mfma_f32_16x16x32_bf16 v[88:91], v[156:159], v[204:207], v[88:91]
	v_mfma_f32_16x16x32_bf16 v[132:135], v[152:155], v[184:187], v[132:135]
	v_mfma_f32_16x16x32_bf16 v[128:131], v[160:163], v[184:187], v[128:131]
	v_mfma_f32_16x16x32_bf16 v[124:127], v[152:155], v[192:195], v[124:127]
	v_mfma_f32_16x16x32_bf16 v[120:123], v[160:163], v[192:195], v[120:123]
	v_mfma_f32_16x16x32_bf16 v[108:111], v[152:155], v[200:203], v[108:111]
	v_mfma_f32_16x16x32_bf16 v[104:107], v[160:163], v[200:203], v[104:107]
	v_mfma_f32_16x16x32_bf16 v[92:95], v[152:155], v[208:211], v[92:95]
	v_mfma_f32_16x16x32_bf16 v[88:91], v[160:163], v[208:211], v[88:91]
	s_setprio 0
	s_setprio 1
	v_mfma_f32_16x16x32_bf16 v[116:119], v[164:167], v[180:183], v[116:119]
	v_mfma_f32_16x16x32_bf16 v[112:115], v[172:175], v[180:183], v[112:115]
	v_mfma_f32_16x16x32_bf16 v[100:103], v[164:167], v[188:191], v[100:103]
	v_mfma_f32_16x16x32_bf16 v[96:99], v[172:175], v[188:191], v[96:99]
	v_mfma_f32_16x16x32_bf16 v[84:87], v[164:167], v[196:199], v[84:87]
	v_mfma_f32_16x16x32_bf16 v[80:83], v[172:175], v[196:199], v[80:83]
	v_mfma_f32_16x16x32_bf16 v[76:79], v[164:167], v[204:207], v[76:79]
	v_mfma_f32_16x16x32_bf16 v[72:75], v[172:175], v[204:207], v[72:75]
	v_mfma_f32_16x16x32_bf16 v[116:119], v[168:171], v[184:187], v[116:119]
	v_mfma_f32_16x16x32_bf16 v[112:115], v[176:179], v[184:187], v[112:115]
	v_mfma_f32_16x16x32_bf16 v[100:103], v[168:171], v[192:195], v[100:103]
	v_mfma_f32_16x16x32_bf16 v[96:99], v[176:179], v[192:195], v[96:99]
	v_mfma_f32_16x16x32_bf16 v[84:87], v[168:171], v[200:203], v[84:87]
	v_mfma_f32_16x16x32_bf16 v[80:83], v[176:179], v[200:203], v[80:83]
	v_mfma_f32_16x16x32_bf16 v[76:79], v[168:171], v[208:211], v[76:79]
	v_mfma_f32_16x16x32_bf16 v[72:75], v[176:179], v[208:211], v[72:75]
	s_setprio 0
	s_barrier
; #define PG8_STAGE(bufoff, gbase, voff) do { _Pragma("unroll") for (int _i = 0; _i < 2; ++_i) \
;         __builtin_amdgcn_global_load_lds((const unsigned*)((const char*)(gbase) + (voff)[_i]), (PG8_LAS unsigned*)(lds + (bufoff) + ldsw + _i * 8192), 16, 0, 0); } while (0)
; #define PG8_LDA(dst, b, h) do { _Pragma("unroll") for (int m = 0; m < 4; ++m) _Pragma("unroll") for (int k = 0; k < 2; ++k) dst[m][k] = *(const PG8_LAS bf16x8*)(lds + PG8_SA(b, h) + aoff + m * 2048 + k * 1024); } while (0)
; #define PG8_MMA(ai, bj, At, Bt) do { __builtin_amdgcn_s_setprio(1); _Pragma("unroll") for (int m = 0; m < 4; ++m) _Pragma("unroll") for (int n = 0; n < 2; ++n) _Pragma("unroll") for (int k = 0; k < 2; ++k) \
;         acc[ai][bj][m][n] = __builtin_amdgcn_mfma_f32_16x16x32_bf16(Bt[n][k], At[m][k], acc[ai][bj][m][n], 0, 0, 0); __builtin_amdgcn_s_setprio(0); } while (0)
; #define PG8_WAIT_V(n) asm volatile("s_waitcnt vmcnt(" #n ")" ::: "memory")
; #define PG8_WAIT_L(n) asm volatile("s_waitcnt lgkmcnt(" #n ")" ::: "memory")
; #define PG8_BAR __builtin_amdgcn_s_barrier()
; #define PG8_SCHED __builtin_amdgcn_sched_barrier(0)
; template <class Epi, class Sched, bool ALIGN_EPI = false, bool SP2 = false, bool ABLK = false, bool BBLK = false>
; __device__ __forceinline__ void gemm_phase(PG8_LAS unsigned char* lds, const Gemm g, const Sched& S, const Epi& E) {
;     ...
;             PG8_LDA(At, 1, 1); PG8_STAGE(PG8_SB(1, 0), b3, voffB); PG8_STAGE(PG8_SB(1, 1), b3 + hstepB, voffB); PG8_STAGE(PG8_SA(1, 0), a3, voffA);
;             PG8_WAIT_V(8); PG8_WAIT_L(0); PG8_BAR; PG8_MMA(1, 0, At, B0); PG8_MMA(1, 1, At, B1); PG8_BAR; PG8_SCHED;
	s_add_u32 s28, s26, 0x8000
	s_addc_u32 s29, s27, 0
	s_add_i32 s68, s68, s34
	s_mov_b32 m0, s68
	ds_read_b128 v[180:183], v150 offset:49152
	ds_read_b128 v[184:187], v150 offset:50176
	ds_read_b128 v[188:191], v150 offset:51200
	ds_read_b128 v[192:195], v150 offset:52224
	ds_read_b128 v[196:199], v150 offset:53248
	ds_read_b128 v[200:203], v150 offset:54272
	ds_read_b128 v[204:207], v150 offset:55296
	ds_read_b128 v[208:211], v150 offset:56320
	global_load_lds_dwordx4 v138, s[28:29]
	s_add_i32 m0, s68, 0x2000
	s_add_u32 s26, s26, 0xc000
	s_addc_u32 s27, s27, 0
	global_load_lds_dwordx4 v142, s[28:29]
	s_add_i32 s28, s69, s34
	s_mov_b32 m0, s28
	s_nop 0
	global_load_lds_dwordx4 v138, s[26:27]
	s_add_i32 m0, s28, 0x2000
	s_nop 0
	global_load_lds_dwordx4 v142, s[26:27]
	s_mov_b32 m0, s64
	s_nop 0
	global_load_lds_dwordx4 v136, s[24:25]
	s_mov_b32 m0, s65
	s_nop 0
	global_load_lds_dwordx4 v140, s[24:25]
	s_waitcnt vmcnt(8)
	s_waitcnt lgkmcnt(0)
	v_mfma_f32_16x16x32_bf16 v[68:71], v[52:55], v[180:183], v[68:71]
	v_mfma_f32_16x16x32_bf16 v[64:67], v[156:159], v[180:183], v[64:67]
	v_mfma_f32_16x16x32_bf16 v[60:63], v[52:55], v[188:191], v[60:63]
	v_mfma_f32_16x16x32_bf16 v[56:59], v[156:159], v[188:191], v[56:59]
	s_barrier
	s_setprio 1
	v_mfma_f32_16x16x32_bf16 v[44:47], v[52:55], v[196:199], v[44:47]
	v_mfma_f32_16x16x32_bf16 v[40:43], v[156:159], v[196:199], v[40:43]
	v_mfma_f32_16x16x32_bf16 v[24:27], v[52:55], v[204:207], v[24:27]
	v_mfma_f32_16x16x32_bf16 v[20:23], v[156:159], v[204:207], v[20:23]
	v_mfma_f32_16x16x32_bf16 v[68:71], v[152:155], v[184:187], v[68:71]
	v_mfma_f32_16x16x32_bf16 v[64:67], v[160:163], v[184:187], v[64:67]
	v_mfma_f32_16x16x32_bf16 v[60:63], v[152:155], v[192:195], v[60:63]
	v_mfma_f32_16x16x32_bf16 v[56:59], v[160:163], v[192:195], v[56:59]
	v_mfma_f32_16x16x32_bf16 v[44:47], v[152:155], v[200:203], v[44:47]
	v_mfma_f32_16x16x32_bf16 v[40:43], v[160:163], v[200:203], v[40:43]
	v_mfma_f32_16x16x32_bf16 v[24:27], v[152:155], v[208:211], v[24:27]
	v_mfma_f32_16x16x32_bf16 v[20:23], v[160:163], v[208:211], v[20:23]
	s_setprio 0
	s_setprio 1
	v_mfma_f32_16x16x32_bf16 v[36:39], v[164:167], v[180:183], v[36:39]
	v_mfma_f32_16x16x32_bf16 v[52:55], v[168:171], v[184:187], v[36:39]
	v_mfma_f32_16x16x32_bf16 v[36:39], v[172:175], v[180:183], v[48:51]
	v_mfma_f32_16x16x32_bf16 v[32:35], v[164:167], v[188:191], v[32:35]
	v_mfma_f32_16x16x32_bf16 v[28:31], v[172:175], v[188:191], v[28:31]
	v_mfma_f32_16x16x32_bf16 v[16:19], v[164:167], v[196:199], v[16:19]
	v_mfma_f32_16x16x32_bf16 v[12:15], v[172:175], v[196:199], v[12:15]
	v_mfma_f32_16x16x32_bf16 v[8:11], v[164:167], v[204:207], v[8:11]
	v_mfma_f32_16x16x32_bf16 v[4:7], v[172:175], v[204:207], v[4:7]
	v_mfma_f32_16x16x32_bf16 v[48:51], v[176:179], v[184:187], v[36:39]
	v_mfma_f32_16x16x32_bf16 v[32:35], v[168:171], v[192:195], v[32:35]
	v_mfma_f32_16x16x32_bf16 v[28:31], v[176:179], v[192:195], v[28:31]
	v_mfma_f32_16x16x32_bf16 v[16:19], v[168:171], v[200:203], v[16:19]
	v_mfma_f32_16x16x32_bf16 v[12:15], v[176:179], v[200:203], v[12:15]
	v_mfma_f32_16x16x32_bf16 v[8:11], v[168:171], v[208:211], v[8:11]
	v_mfma_f32_16x16x32_bf16 v[4:7], v[176:179], v[208:211], v[4:7]
	s_setprio 0
	s_barrier
	s_add_i32 s13, s13, 2
	s_add_u32 s22, s22, 0x10000
	s_addc_u32 s23, s23, 0
	s_add_u32 s82, s82, 0x10000
	s_addc_u32 vcc_lo, vcc_lo, 0
	s_cmp_gt_u32 s13, 29
	s_cbranch_scc0 .LBB0_2111
	s_and_b64 vcc, exec, s[6:7]
	s_movk_i32 s77, 0x1000
	s_cbranch_vccz .LBB0_2114
	s_barrier
